# packed fp32 ops split also in EpiMerge and the mix-out EpiResid (bit-identical)
# baseline (speedup 1.0000x reference)
; DI unsigned pk2(float lo, float hi) { f32x2 v = {lo, hi}; hbf2 r = __builtin_convertvector(v, hbf2); return __builtin_bit_cast(unsigned, r); }
; DI float fast_rcp(float x) { return __builtin_amdgcn_rcpf(x); }
;     DI void operator()(f32x4 (&acc)[2][2][4][2], const Unit& u, int wr, int wc, int fr, int fq, LAS unsigned char* lds) const {
;     ...
;             for (int m = 0; m < 4; ++m) {
;                 const int row = row0 + ai * 128 + m * 16;
; #pragma unroll
;                 for (int bj = 0; bj < 2; ++bj) {
;                     const u32x4 gb = gbv[m][bj];
;                     float gbf[8];
; #pragma unroll
;                     for (int q = 0; q < 4; ++q) { gbf[2 * q] = __uint_as_float(gb[q] << 16); gbf[2 * q + 1] = __uint_as_float(gb[q] & 0xffff0000u); }
;                     if (s == 0) {
;                         const u32x4 ga = gav[m][bj];
; #pragma unroll
;                         for (int q = 0; q < 4; ++q) {
;                             const float a0 = __uint_as_float(ga[q] << 16), a1 = __uint_as_float(ga[q] & 0xffff0000u);
;                             const int n = q >> 1, j = (q & 1) * 2;
;                             acc[ai][bj][m][n][j] *= a0 * fast_rcp(gbf[2 * q]); acc[ai][bj][m][n][j + 1] *= a1 * fast_rcp(gbf[2 * q + 1]);
;                         }
;                     } else {
;                         u32x4 w;
; #pragma unroll
;                         for (int q = 0; q < 4; ++q) { const int n = q >> 1, j = (q & 1) * 2; w[q] = pk2(acc[ai][bj][m][n][j] * gbf[2 * q], acc[ai][bj][m][n][j + 1] * gbf[2 * q + 1]); }
;                         *(u32x4*)(MB + (size_t)row * DM + col0 + bj * 128) = w;
;                     }
.LBB0_1505:
	v_lshlrev_b64 v[226:227], 11, v[206:207]
	s_waitcnt vmcnt(0)
	v_lshlrev_b32_e32 v220, 16, v190
	v_and_b32_e32 v221, 0xffff0000, v190
	v_cndmask_b32_e64 v190, 0, 1, s[16:17]
	v_lshlrev_b32_e32 v218, 16, v191
	v_and_b32_e32 v219, 0xffff0000, v191
	v_cmp_ne_u32_e64 s[40:41], 1, v190
	v_lshl_add_u64 v[190:191], s[74:75], 0, v[226:227]
	v_lshlrev_b32_e32 v216, 16, v192
	v_and_b32_e32 v217, 0xffff0000, v192
	v_lshlrev_b32_e32 v192, 16, v193
	v_and_b32_e32 v193, 0xffff0000, v193
	s_mov_b64 s[18:19], -1
	s_andn2_b64 vcc, exec, s[16:17]
	v_lshl_add_u64 v[190:191], v[204:205], 1, v[190:191]
	s_cbranch_vccnz .LBB0_1507
	v_mul_f32_e32 v226, v126, v220
	v_mul_f32_e32 v227, v127, v221
	s_mov_b64 s[18:19], 0
	v_cvt_pk_bf16_f32 v236, v226, v227
	v_mul_f32_e32 v226, v128, v218
	v_mul_f32_e32 v227, v129, v219
	s_nop 0
	v_cvt_pk_bf16_f32 v237, v226, v227
	v_mul_f32_e32 v226, v122, v216
	v_mul_f32_e32 v227, v123, v217
	s_nop 0
	v_cvt_pk_bf16_f32 v238, v226, v227
	v_mul_f32_e32 v226, v124, v192
	v_mul_f32_e32 v227, v125, v193
	s_nop 0
	v_cvt_pk_bf16_f32 v239, v226, v227
	global_store_dwordx4 v[190:191], v[236:239], off
.LBB0_1507:
	s_andn2_b64 vcc, exec, s[18:19]
	s_cbranch_vccnz .LBB0_1509
	v_rcp_f32_e32 v220, v220
	v_rcp_f32_e32 v221, v221
	v_rcp_f32_e32 v218, v218
	v_rcp_f32_e32 v219, v219
	v_lshlrev_b32_e32 v226, 16, v158
	v_and_b32_e32 v227, 0xffff0000, v158
	v_mul_f32_e32 v220, v220, v226
	v_mul_f32_e32 v221, v221, v227
	v_rcp_f32_e32 v216, v216
	v_rcp_f32_e32 v217, v217
	v_mul_f32_e32 v126, v126, v220
	v_mul_f32_e32 v127, v127, v221
	v_lshlrev_b32_e32 v220, 16, v159
	v_and_b32_e32 v221, 0xffff0000, v159
	v_mul_f32_e32 v218, v218, v220
	v_mul_f32_e32 v219, v219, v221
	v_rcp_f32_e32 v192, v192
	v_rcp_f32_e32 v193, v193
	v_mul_f32_e32 v128, v128, v218
	v_mul_f32_e32 v129, v129, v219
	v_lshlrev_b32_e32 v218, 16, v160
	v_and_b32_e32 v219, 0xffff0000, v160
	v_mul_f32_e32 v216, v216, v218
	v_mul_f32_e32 v217, v217, v219
	s_nop 0
	v_mul_f32_e32 v122, v122, v216
	v_mul_f32_e32 v123, v123, v217
	v_lshlrev_b32_e32 v216, 16, v161
	v_and_b32_e32 v217, 0xffff0000, v161
	v_mul_f32_e32 v192, v192, v216
	v_mul_f32_e32 v193, v193, v217
	s_nop 0
	v_mul_f32_e32 v124, v124, v192
	v_mul_f32_e32 v125, v125, v193
.LBB0_1509:
	v_lshlrev_b32_e32 v218, 16, v186
	v_and_b32_e32 v219, 0xffff0000, v186
	v_lshlrev_b32_e32 v216, 16, v187
	v_and_b32_e32 v217, 0xffff0000, v187
	v_lshlrev_b32_e32 v192, 16, v188
	v_and_b32_e32 v193, 0xffff0000, v188
	v_lshlrev_b32_e32 v186, 16, v189
	v_and_b32_e32 v187, 0xffff0000, v189
	s_and_b64 vcc, exec, s[40:41]
	s_mov_b64 s[16:17], -1
	s_cbranch_vccnz .LBB0_1511
	v_mul_f32_e32 v188, v92, v218
	v_mul_f32_e32 v189, v93, v219
	s_mov_b64 s[16:17], 0
	v_cvt_pk_bf16_f32 v236, v188, v189
	v_mul_f32_e32 v188, v94, v216
	v_mul_f32_e32 v189, v95, v217
	s_nop 0
	v_cvt_pk_bf16_f32 v237, v188, v189
	v_mul_f32_e32 v188, v88, v192
	v_mul_f32_e32 v189, v89, v193
	s_nop 0
	v_cvt_pk_bf16_f32 v238, v188, v189
	v_mul_f32_e32 v188, v90, v186
	v_mul_f32_e32 v189, v91, v187
	s_nop 0
	v_cvt_pk_bf16_f32 v239, v188, v189
	global_store_dwordx4 v[190:191], v[236:239], off offset:256
.LBB0_1511:
	s_andn2_b64 vcc, exec, s[16:17]
	s_cbranch_vccnz .LBB0_1513
	v_rcp_f32_e32 v188, v218
	v_rcp_f32_e32 v189, v219
	v_lshlrev_b32_e32 v190, 16, v154
	v_and_b32_e32 v191, 0xffff0000, v154
	v_rcp_f32_e32 v186, v186
	v_mul_f32_e32 v188, v188, v190
	v_mul_f32_e32 v189, v189, v191
	v_rcp_f32_e32 v190, v216
	v_rcp_f32_e32 v191, v217
	v_mul_f32_e32 v92, v92, v188
	v_mul_f32_e32 v93, v93, v189
	v_lshlrev_b32_e32 v188, 16, v155
	v_and_b32_e32 v189, 0xffff0000, v155
	v_mul_f32_e32 v188, v190, v188
	v_mul_f32_e32 v189, v191, v189
	v_rcp_f32_e32 v190, v192
	v_rcp_f32_e32 v191, v193
	v_rcp_f32_e32 v187, v187
	v_mul_f32_e32 v94, v94, v188
	v_mul_f32_e32 v95, v95, v189
	v_lshlrev_b32_e32 v188, 16, v156
	v_and_b32_e32 v189, 0xffff0000, v156
	v_mul_f32_e32 v188, v190, v188
	v_mul_f32_e32 v189, v191, v189
	s_nop 0
	v_mul_f32_e32 v88, v88, v188
	v_mul_f32_e32 v89, v89, v189
	v_lshlrev_b32_e32 v188, 16, v157
	v_and_b32_e32 v189, 0xffff0000, v157
	v_mul_f32_e32 v186, v186, v188
	v_mul_f32_e32 v187, v187, v189
	s_nop 0
	v_mul_f32_e32 v90, v90, v186
	v_mul_f32_e32 v91, v91, v187
.LBB0_1513:
	v_lshlrev_b64 v[192:193], 11, v[214:215]
	v_lshlrev_b32_e32 v190, 16, v182
	v_and_b32_e32 v191, 0xffff0000, v182
	v_lshlrev_b32_e32 v188, 16, v183
	v_and_b32_e32 v189, 0xffff0000, v183
	v_lshl_add_u64 v[182:183], s[74:75], 0, v[192:193]
	v_lshlrev_b32_e32 v186, 16, v184
	v_and_b32_e32 v187, 0xffff0000, v184
	v_lshlrev_b32_e32 v184, 16, v185
	v_and_b32_e32 v185, 0xffff0000, v185
	s_mov_b64 s[16:17], -1
	s_and_b64 vcc, exec, s[40:41]
	v_lshl_add_u64 v[182:183], v[204:205], 1, v[182:183]
	s_cbranch_vccnz .LBB0_1515
	v_mul_f32_e32 v192, v118, v190
	v_mul_f32_e32 v193, v119, v191
	s_mov_b64 s[16:17], 0
	v_cvt_pk_bf16_f32 v214, v192, v193
	v_mul_f32_e32 v192, v120, v188
	v_mul_f32_e32 v193, v121, v189
	s_nop 0
	v_cvt_pk_bf16_f32 v215, v192, v193
	v_mul_f32_e32 v192, v114, v186
	v_mul_f32_e32 v193, v115, v187
	s_nop 0
	v_cvt_pk_bf16_f32 v216, v192, v193
	v_mul_f32_e32 v192, v116, v184
	v_mul_f32_e32 v193, v117, v185
	s_nop 0
	v_cvt_pk_bf16_f32 v217, v192, v193
	global_store_dwordx4 v[182:183], v[214:217], off
; DI unsigned pk2(float lo, float hi) { f32x2 v = {lo, hi}; hbf2 r = __builtin_convertvector(v, hbf2); return __builtin_bit_cast(unsigned, r); }
; DI float fast_rcp(float x) { return __builtin_amdgcn_rcpf(x); }
;     DI void operator()(f32x4 (&acc)[2][2][4][2], const Unit& u, int wr, int wc, int fr, int fq, LAS unsigned char* lds) const {
;     ...
;             for (int m = 0; m < 4; ++m) {
;                 const int row = row0 + ai * 128 + m * 16;
; #pragma unroll
;                 for (int bj = 0; bj < 2; ++bj) {
;                     const u32x4 gb = gbv[m][bj];
;                     float gbf[8];
; #pragma unroll
;                     for (int q = 0; q < 4; ++q) { gbf[2 * q] = __uint_as_float(gb[q] << 16); gbf[2 * q + 1] = __uint_as_float(gb[q] & 0xffff0000u); }
;                     if (s == 0) {
;                         const u32x4 ga = gav[m][bj];
; #pragma unroll
;                         for (int q = 0; q < 4; ++q) {
;                             const float a0 = __uint_as_float(ga[q] << 16), a1 = __uint_as_float(ga[q] & 0xffff0000u);
;                             const int n = q >> 1, j = (q & 1) * 2;
;                             acc[ai][bj][m][n][j] *= a0 * fast_rcp(gbf[2 * q]); acc[ai][bj][m][n][j + 1] *= a1 * fast_rcp(gbf[2 * q + 1]);
;                         }
;                     } else {
;                         u32x4 w;
; #pragma unroll
;                         for (int q = 0; q < 4; ++q) { const int n = q >> 1, j = (q & 1) * 2; w[q] = pk2(acc[ai][bj][m][n][j] * gbf[2 * q], acc[ai][bj][m][n][j + 1] * gbf[2 * q + 1]); }
;                         *(u32x4*)(MB + (size_t)row * DM + col0 + bj * 128) = w;
;                     }
.LBB0_1515:
	s_andn2_b64 vcc, exec, s[16:17]
	s_cbranch_vccnz .LBB0_1517
	v_rcp_f32_e32 v190, v190
	v_rcp_f32_e32 v191, v191
	v_rcp_f32_e32 v188, v188
	v_rcp_f32_e32 v189, v189
	v_lshlrev_b32_e32 v192, 16, v150
	v_and_b32_e32 v193, 0xffff0000, v150
	v_mul_f32_e32 v190, v190, v192
	v_mul_f32_e32 v191, v191, v193
	v_rcp_f32_e32 v186, v186
	v_rcp_f32_e32 v187, v187
	v_mul_f32_e32 v118, v118, v190
	v_mul_f32_e32 v119, v119, v191
	v_lshlrev_b32_e32 v190, 16, v151
	v_and_b32_e32 v191, 0xffff0000, v151
	v_mul_f32_e32 v188, v188, v190
	v_mul_f32_e32 v189, v189, v191
	v_rcp_f32_e32 v184, v184
	v_rcp_f32_e32 v185, v185
	v_mul_f32_e32 v120, v120, v188
	v_mul_f32_e32 v121, v121, v189
	v_lshlrev_b32_e32 v188, 16, v152
	v_and_b32_e32 v189, 0xffff0000, v152
	v_mul_f32_e32 v186, v186, v188
	v_mul_f32_e32 v187, v187, v189
	s_nop 0
	v_mul_f32_e32 v114, v114, v186
	v_mul_f32_e32 v115, v115, v187
	v_lshlrev_b32_e32 v186, 16, v153
	v_and_b32_e32 v187, 0xffff0000, v153
	v_mul_f32_e32 v184, v184, v186
	v_mul_f32_e32 v185, v185, v187
	s_nop 0
	v_mul_f32_e32 v116, v116, v184
	v_mul_f32_e32 v117, v117, v185
.LBB0_1517:
	v_lshlrev_b32_e32 v188, 16, v178
	v_and_b32_e32 v189, 0xffff0000, v178
	v_lshlrev_b32_e32 v186, 16, v179
	v_and_b32_e32 v187, 0xffff0000, v179
	v_lshlrev_b32_e32 v184, 16, v180
	v_and_b32_e32 v185, 0xffff0000, v180
	v_lshlrev_b32_e32 v178, 16, v181
	v_and_b32_e32 v179, 0xffff0000, v181
	s_and_b64 vcc, exec, s[40:41]
	s_mov_b64 s[16:17], -1
	s_cbranch_vccnz .LBB0_1519
	v_mul_f32_e32 v180, v84, v188
	v_mul_f32_e32 v181, v85, v189
	s_mov_b64 s[16:17], 0
	v_cvt_pk_bf16_f32 v190, v180, v181
	v_mul_f32_e32 v180, v86, v186
	v_mul_f32_e32 v181, v87, v187
	s_nop 0
	v_cvt_pk_bf16_f32 v191, v180, v181
	v_mul_f32_e32 v180, v80, v184
	v_mul_f32_e32 v181, v81, v185
	s_nop 0
	v_cvt_pk_bf16_f32 v192, v180, v181
	v_mul_f32_e32 v180, v82, v178
	v_mul_f32_e32 v181, v83, v179
	s_nop 0
	v_cvt_pk_bf16_f32 v193, v180, v181
	global_store_dwordx4 v[182:183], v[190:193], off offset:256
.LBB0_1519:
	s_andn2_b64 vcc, exec, s[16:17]
	s_cbranch_vccnz .LBB0_1521
	v_rcp_f32_e32 v180, v188
	v_rcp_f32_e32 v181, v189
	v_lshlrev_b32_e32 v182, 16, v146
	v_and_b32_e32 v183, 0xffff0000, v146
	v_rcp_f32_e32 v178, v178
	v_mul_f32_e32 v180, v180, v182
	v_mul_f32_e32 v181, v181, v183
	v_rcp_f32_e32 v182, v186
	v_rcp_f32_e32 v183, v187
	v_mul_f32_e32 v84, v84, v180
	v_mul_f32_e32 v85, v85, v181
	v_lshlrev_b32_e32 v180, 16, v147
	v_and_b32_e32 v181, 0xffff0000, v147
	v_mul_f32_e32 v180, v182, v180
	v_mul_f32_e32 v181, v183, v181
	v_rcp_f32_e32 v182, v184
	v_rcp_f32_e32 v183, v185
	v_rcp_f32_e32 v179, v179
	v_mul_f32_e32 v86, v86, v180
	v_mul_f32_e32 v87, v87, v181
	v_lshlrev_b32_e32 v180, 16, v148
	v_and_b32_e32 v181, 0xffff0000, v148
	v_mul_f32_e32 v180, v182, v180
	v_mul_f32_e32 v181, v183, v181
	s_nop 0
	v_mul_f32_e32 v80, v80, v180
	v_mul_f32_e32 v81, v81, v181
	v_lshlrev_b32_e32 v180, 16, v149
	v_and_b32_e32 v181, 0xffff0000, v149
	v_mul_f32_e32 v178, v178, v180
	v_mul_f32_e32 v179, v179, v181
	s_nop 0
	v_mul_f32_e32 v82, v82, v178
	v_mul_f32_e32 v83, v83, v179
.LBB0_1521:
	v_lshlrev_b64 v[184:185], 11, v[212:213]
	v_lshlrev_b32_e32 v182, 16, v174
	v_and_b32_e32 v183, 0xffff0000, v174
	v_lshlrev_b32_e32 v180, 16, v175
	v_and_b32_e32 v181, 0xffff0000, v175
	v_lshl_add_u64 v[174:175], s[74:75], 0, v[184:185]
	v_lshlrev_b32_e32 v178, 16, v176
	v_and_b32_e32 v179, 0xffff0000, v176
	v_lshlrev_b32_e32 v176, 16, v177
	v_and_b32_e32 v177, 0xffff0000, v177
	s_mov_b64 s[16:17], -1
	s_and_b64 vcc, exec, s[40:41]
	v_lshl_add_u64 v[174:175], v[204:205], 1, v[174:175]
	s_cbranch_vccnz .LBB0_1523
	v_mul_f32_e32 v184, v110, v182
	v_mul_f32_e32 v185, v111, v183
	v_mul_f32_e32 v186, v112, v180
	v_mul_f32_e32 v187, v113, v181
	v_cvt_pk_bf16_f32 v184, v184, v185
	v_cvt_pk_bf16_f32 v185, v186, v187
	v_mul_f32_e32 v186, v106, v178
	v_mul_f32_e32 v187, v107, v179
	v_mul_f32_e32 v188, v108, v176
	v_mul_f32_e32 v189, v109, v177
	v_cvt_pk_bf16_f32 v186, v186, v187
	v_cvt_pk_bf16_f32 v187, v188, v189
	s_mov_b64 s[16:17], 0
	global_store_dwordx4 v[174:175], v[184:187], off
.LBB0_1523:
	s_andn2_b64 vcc, exec, s[16:17]
	s_cbranch_vccnz .LBB0_1525
	v_rcp_f32_e32 v182, v182
	v_rcp_f32_e32 v183, v183
	v_rcp_f32_e32 v180, v180
	v_rcp_f32_e32 v181, v181
	v_lshlrev_b32_e32 v184, 16, v142
	v_and_b32_e32 v185, 0xffff0000, v142
	v_mul_f32_e32 v182, v182, v184
	v_mul_f32_e32 v183, v183, v185
	v_rcp_f32_e32 v178, v178
	v_rcp_f32_e32 v179, v179
	v_mul_f32_e32 v110, v110, v182
	v_mul_f32_e32 v111, v111, v183
	v_lshlrev_b32_e32 v182, 16, v143
	v_and_b32_e32 v183, 0xffff0000, v143
	v_mul_f32_e32 v180, v180, v182
	v_mul_f32_e32 v181, v181, v183
	v_rcp_f32_e32 v176, v176
	v_rcp_f32_e32 v177, v177
	v_mul_f32_e32 v112, v112, v180
	v_mul_f32_e32 v113, v113, v181
	v_lshlrev_b32_e32 v180, 16, v144
	v_and_b32_e32 v181, 0xffff0000, v144
	v_mul_f32_e32 v178, v178, v180
	v_mul_f32_e32 v179, v179, v181
	s_nop 0
	v_mul_f32_e32 v106, v106, v178
	v_mul_f32_e32 v107, v107, v179
	v_lshlrev_b32_e32 v178, 16, v145
	v_and_b32_e32 v179, 0xffff0000, v145
	v_mul_f32_e32 v176, v176, v178
	v_mul_f32_e32 v177, v177, v179
	s_nop 0
	v_mul_f32_e32 v108, v108, v176
	v_mul_f32_e32 v109, v109, v177
; DI unsigned pk2(float lo, float hi) { f32x2 v = {lo, hi}; hbf2 r = __builtin_convertvector(v, hbf2); return __builtin_bit_cast(unsigned, r); }
; DI float fast_rcp(float x) { return __builtin_amdgcn_rcpf(x); }
;     DI void operator()(f32x4 (&acc)[2][2][4][2], const Unit& u, int wr, int wc, int fr, int fq, LAS unsigned char* lds) const {
;     ...
;             for (int m = 0; m < 4; ++m) {
;                 const int row = row0 + ai * 128 + m * 16;
; #pragma unroll
;                 for (int bj = 0; bj < 2; ++bj) {
;                     const u32x4 gb = gbv[m][bj];
;                     float gbf[8];
; #pragma unroll
;                     for (int q = 0; q < 4; ++q) { gbf[2 * q] = __uint_as_float(gb[q] << 16); gbf[2 * q + 1] = __uint_as_float(gb[q] & 0xffff0000u); }
;                     if (s == 0) {
;                         const u32x4 ga = gav[m][bj];
; #pragma unroll
;                         for (int q = 0; q < 4; ++q) {
;                             const float a0 = __uint_as_float(ga[q] << 16), a1 = __uint_as_float(ga[q] & 0xffff0000u);
;                             const int n = q >> 1, j = (q & 1) * 2;
;                             acc[ai][bj][m][n][j] *= a0 * fast_rcp(gbf[2 * q]); acc[ai][bj][m][n][j + 1] *= a1 * fast_rcp(gbf[2 * q + 1]);
;                         }
;                     } else {
;                         u32x4 w;
; #pragma unroll
;                         for (int q = 0; q < 4; ++q) { const int n = q >> 1, j = (q & 1) * 2; w[q] = pk2(acc[ai][bj][m][n][j] * gbf[2 * q], acc[ai][bj][m][n][j + 1] * gbf[2 * q + 1]); }
;                         *(u32x4*)(MB + (size_t)row * DM + col0 + bj * 128) = w;
;                     }
.LBB0_1525:
	v_lshlrev_b32_e32 v180, 16, v170
	v_and_b32_e32 v181, 0xffff0000, v170
	v_lshlrev_b32_e32 v178, 16, v171
	v_and_b32_e32 v179, 0xffff0000, v171
	v_lshlrev_b32_e32 v176, 16, v172
	v_and_b32_e32 v177, 0xffff0000, v172
	v_lshlrev_b32_e32 v170, 16, v173
	v_and_b32_e32 v171, 0xffff0000, v173
	s_and_b64 vcc, exec, s[40:41]
	s_mov_b64 s[16:17], -1
	s_cbranch_vccnz .LBB0_1527
	v_mul_f32_e32 v172, v76, v180
	v_mul_f32_e32 v173, v77, v181
	s_mov_b64 s[16:17], 0
	v_cvt_pk_bf16_f32 v182, v172, v173
	v_mul_f32_e32 v172, v78, v178
	v_mul_f32_e32 v173, v79, v179
	s_nop 0
	v_cvt_pk_bf16_f32 v183, v172, v173
	v_mul_f32_e32 v172, v72, v176
	v_mul_f32_e32 v173, v73, v177
	s_nop 0
	v_cvt_pk_bf16_f32 v184, v172, v173
	v_mul_f32_e32 v172, v74, v170
	v_mul_f32_e32 v173, v75, v171
	s_nop 0
	v_cvt_pk_bf16_f32 v185, v172, v173
	global_store_dwordx4 v[174:175], v[182:185], off offset:256
.LBB0_1527:
	s_andn2_b64 vcc, exec, s[16:17]
	s_cbranch_vccnz .LBB0_1529
	v_rcp_f32_e32 v172, v180
	v_rcp_f32_e32 v173, v181
	v_lshlrev_b32_e32 v174, 16, v138
	v_and_b32_e32 v175, 0xffff0000, v138
	v_rcp_f32_e32 v170, v170
	v_mul_f32_e32 v172, v172, v174
	v_mul_f32_e32 v173, v173, v175
	v_rcp_f32_e32 v174, v178
	v_rcp_f32_e32 v175, v179
	v_mul_f32_e32 v76, v76, v172
	v_mul_f32_e32 v77, v77, v173
	v_lshlrev_b32_e32 v172, 16, v139
	v_and_b32_e32 v173, 0xffff0000, v139
	v_mul_f32_e32 v172, v174, v172
	v_mul_f32_e32 v173, v175, v173
	v_rcp_f32_e32 v174, v176
	v_rcp_f32_e32 v175, v177
	v_rcp_f32_e32 v171, v171
	v_mul_f32_e32 v78, v78, v172
	v_mul_f32_e32 v79, v79, v173
	v_lshlrev_b32_e32 v172, 16, v140
	v_and_b32_e32 v173, 0xffff0000, v140
	v_mul_f32_e32 v172, v174, v172
	v_mul_f32_e32 v173, v175, v173
	s_nop 0
	v_mul_f32_e32 v72, v72, v172
	v_mul_f32_e32 v73, v73, v173
	v_lshlrev_b32_e32 v172, 16, v141
	v_and_b32_e32 v173, 0xffff0000, v141
	v_mul_f32_e32 v170, v170, v172
	v_mul_f32_e32 v171, v171, v173
	s_nop 0
	v_mul_f32_e32 v74, v74, v170
	v_mul_f32_e32 v75, v75, v171
.LBB0_1529:
	v_lshlrev_b64 v[176:177], 11, v[210:211]
	v_lshlrev_b32_e32 v174, 16, v166
	v_and_b32_e32 v175, 0xffff0000, v166
	v_lshlrev_b32_e32 v172, 16, v167
	v_and_b32_e32 v173, 0xffff0000, v167
	v_lshl_add_u64 v[166:167], s[74:75], 0, v[176:177]
	v_lshlrev_b32_e32 v170, 16, v168
	v_and_b32_e32 v171, 0xffff0000, v168
	v_lshlrev_b32_e32 v168, 16, v169
	v_and_b32_e32 v169, 0xffff0000, v169
	s_mov_b64 s[16:17], -1
	s_and_b64 vcc, exec, s[40:41]
	v_lshl_add_u64 v[166:167], v[204:205], 1, v[166:167]
	s_cbranch_vccnz .LBB0_1531
	v_mul_f32_e32 v176, v102, v174
	v_mul_f32_e32 v177, v103, v175
	v_mul_f32_e32 v178, v104, v172
	v_mul_f32_e32 v179, v105, v173
	v_cvt_pk_bf16_f32 v176, v176, v177
	v_cvt_pk_bf16_f32 v177, v178, v179
	v_mul_f32_e32 v178, v98, v170
	v_mul_f32_e32 v179, v99, v171
	v_mul_f32_e32 v180, v100, v168
	v_mul_f32_e32 v181, v101, v169
	v_cvt_pk_bf16_f32 v178, v178, v179
	v_cvt_pk_bf16_f32 v179, v180, v181
	s_mov_b64 s[16:17], 0
	global_store_dwordx4 v[166:167], v[176:179], off
.LBB0_1531:
	s_andn2_b64 vcc, exec, s[16:17]
	s_cbranch_vccnz .LBB0_1533
	v_rcp_f32_e32 v174, v174
	v_rcp_f32_e32 v175, v175
	v_rcp_f32_e32 v172, v172
	v_rcp_f32_e32 v173, v173
	v_lshlrev_b32_e32 v176, 16, v134
	v_and_b32_e32 v177, 0xffff0000, v134
	v_mul_f32_e32 v174, v174, v176
	v_mul_f32_e32 v175, v175, v177
	v_rcp_f32_e32 v170, v170
	v_rcp_f32_e32 v171, v171
	v_mul_f32_e32 v102, v102, v174
	v_mul_f32_e32 v103, v103, v175
	v_lshlrev_b32_e32 v174, 16, v135
	v_and_b32_e32 v175, 0xffff0000, v135
	v_mul_f32_e32 v172, v172, v174
	v_mul_f32_e32 v173, v173, v175
	v_rcp_f32_e32 v168, v168
	v_rcp_f32_e32 v169, v169
	v_mul_f32_e32 v104, v104, v172
	v_mul_f32_e32 v105, v105, v173
	v_lshlrev_b32_e32 v172, 16, v136
	v_and_b32_e32 v173, 0xffff0000, v136
	v_mul_f32_e32 v170, v170, v172
	v_mul_f32_e32 v171, v171, v173
	s_nop 0
	v_mul_f32_e32 v98, v98, v170
	v_mul_f32_e32 v99, v99, v171
	v_lshlrev_b32_e32 v170, 16, v137
	v_and_b32_e32 v171, 0xffff0000, v137
	v_mul_f32_e32 v168, v168, v170
	v_mul_f32_e32 v169, v169, v171
	s_nop 0
	v_mul_f32_e32 v100, v100, v168
	v_mul_f32_e32 v101, v101, v169
.LBB0_1533:
	v_lshlrev_b32_e32 v172, 16, v162
	v_and_b32_e32 v173, 0xffff0000, v162
	v_lshlrev_b32_e32 v170, 16, v163
	v_and_b32_e32 v171, 0xffff0000, v163
	v_lshlrev_b32_e32 v168, 16, v164
	v_and_b32_e32 v169, 0xffff0000, v164
	v_lshlrev_b32_e32 v162, 16, v165
	v_and_b32_e32 v163, 0xffff0000, v165
	s_and_b64 vcc, exec, s[40:41]
	s_mov_b64 s[16:17], -1
	s_cbranch_vccnz .LBB0_1535
	v_mul_f32_e32 v164, v68, v172
	v_mul_f32_e32 v165, v69, v173
	s_mov_b64 s[16:17], 0
	v_cvt_pk_bf16_f32 v174, v164, v165
	v_mul_f32_e32 v164, v70, v170
	v_mul_f32_e32 v165, v71, v171
	s_nop 0
	v_cvt_pk_bf16_f32 v175, v164, v165
	v_mul_f32_e32 v164, v64, v168
	v_mul_f32_e32 v165, v65, v169
	s_nop 0
	v_cvt_pk_bf16_f32 v176, v164, v165
	v_mul_f32_e32 v164, v66, v162
	v_mul_f32_e32 v165, v67, v163
	s_nop 0
	v_cvt_pk_bf16_f32 v177, v164, v165
	global_store_dwordx4 v[166:167], v[174:177], off offset:256
.LBB0_1535:
	s_andn2_b64 vcc, exec, s[16:17]
	s_cbranch_vccnz .LBB0_1537
	v_rcp_f32_e32 v164, v172
	v_rcp_f32_e32 v165, v173
	v_lshlrev_b32_e32 v166, 16, v130
	v_and_b32_e32 v167, 0xffff0000, v130
	v_rcp_f32_e32 v162, v162
	v_mul_f32_e32 v164, v164, v166
	v_mul_f32_e32 v165, v165, v167
	v_rcp_f32_e32 v166, v170
	v_rcp_f32_e32 v167, v171
	v_mul_f32_e32 v68, v68, v164
	v_mul_f32_e32 v69, v69, v165
	v_lshlrev_b32_e32 v164, 16, v131
	v_and_b32_e32 v165, 0xffff0000, v131
	v_mul_f32_e32 v164, v166, v164
	v_mul_f32_e32 v165, v167, v165
	v_rcp_f32_e32 v166, v168
	v_rcp_f32_e32 v167, v169
	v_rcp_f32_e32 v163, v163
	v_mul_f32_e32 v70, v70, v164
	v_mul_f32_e32 v71, v71, v165
	v_lshlrev_b32_e32 v164, 16, v132
	v_and_b32_e32 v165, 0xffff0000, v132
	v_mul_f32_e32 v164, v166, v164
	v_mul_f32_e32 v165, v167, v165
	s_nop 0
	v_mul_f32_e32 v64, v64, v164
	v_mul_f32_e32 v65, v65, v165
	v_lshlrev_b32_e32 v164, 16, v133
	v_and_b32_e32 v165, 0xffff0000, v133
	v_mul_f32_e32 v162, v162, v164
	v_mul_f32_e32 v163, v163, v165
	s_nop 0
	v_mul_f32_e32 v66, v66, v162
	v_mul_f32_e32 v67, v67, v163

; DI unsigned pk2(float lo, float hi) { f32x2 v = {lo, hi}; hbf2 r = __builtin_convertvector(v, hbf2); return __builtin_bit_cast(unsigned, r); }
; DI float fast_rcp(float x) { return __builtin_amdgcn_rcpf(x); }
;     DI void operator()(f32x4 (&acc)[2][2][4][2], const Unit& u, int wr, int wc, int fr, int fq, LAS unsigned char* lds) const {
;     ...
;             for (int m = 0; m < 4; ++m) {
;                 const int row = row0 + ai * 128 + m * 16;
; #pragma unroll
;                 for (int bj = 0; bj < 2; ++bj) {
;                     const u32x4 gb = gbv[m][bj];
;                     float gbf[8];
; #pragma unroll
;                     for (int q = 0; q < 4; ++q) { gbf[2 * q] = __uint_as_float(gb[q] << 16); gbf[2 * q + 1] = __uint_as_float(gb[q] & 0xffff0000u); }
;                     if (s == 0) {
;                         const u32x4 ga = gav[m][bj];
; #pragma unroll
;                         for (int q = 0; q < 4; ++q) {
;                             const float a0 = __uint_as_float(ga[q] << 16), a1 = __uint_as_float(ga[q] & 0xffff0000u);
;                             const int n = q >> 1, j = (q & 1) * 2;
;                             acc[ai][bj][m][n][j] *= a0 * fast_rcp(gbf[2 * q]); acc[ai][bj][m][n][j + 1] *= a1 * fast_rcp(gbf[2 * q + 1]);
;                         }
;                     } else {
;                         u32x4 w;
; #pragma unroll
;                         for (int q = 0; q < 4; ++q) { const int n = q >> 1, j = (q & 1) * 2; w[q] = pk2(acc[ai][bj][m][n][j] * gbf[2 * q], acc[ai][bj][m][n][j + 1] * gbf[2 * q + 1]); }
;                         *(u32x4*)(MB + (size_t)row * DM + col0 + bj * 128) = w;
;                     }
.LBB0_1553:
	v_lshlrev_b64 v[218:219], 11, v[214:215]
	s_waitcnt vmcnt(0)
	v_lshlrev_b32_e32 v216, 16, v190
	v_and_b32_e32 v217, 0xffff0000, v190
	v_lshlrev_b32_e32 v214, 16, v191
	v_and_b32_e32 v215, 0xffff0000, v191
	v_lshl_add_u64 v[190:191], s[74:75], 0, v[218:219]
	v_lshlrev_b32_e32 v208, 16, v192
	v_and_b32_e32 v209, 0xffff0000, v192
	v_lshlrev_b32_e32 v192, 16, v193
	v_and_b32_e32 v193, 0xffff0000, v193
	s_mov_b64 s[16:17], -1
	s_and_b64 vcc, exec, s[40:41]
	v_lshl_add_u64 v[190:191], v[204:205], 1, v[190:191]
	s_cbranch_vccnz .LBB0_1555
	v_mul_f32_e32 v218, v60, v216
	v_mul_f32_e32 v219, v61, v217
	v_mul_f32_e32 v220, v62, v214
	v_mul_f32_e32 v221, v63, v215
	v_cvt_pk_bf16_f32 v218, v218, v219
	v_cvt_pk_bf16_f32 v219, v220, v221
	v_mul_f32_e32 v220, v56, v208
	v_mul_f32_e32 v221, v57, v209
	v_mul_f32_e32 v226, v58, v192
	v_mul_f32_e32 v227, v59, v193
	v_cvt_pk_bf16_f32 v220, v220, v221
	v_cvt_pk_bf16_f32 v221, v226, v227
	s_mov_b64 s[16:17], 0
	global_store_dwordx4 v[190:191], v[218:221], off
.LBB0_1555:
	s_andn2_b64 vcc, exec, s[16:17]
	s_cbranch_vccnz .LBB0_1557
	v_rcp_f32_e32 v214, v214
	v_rcp_f32_e32 v215, v215
	v_rcp_f32_e32 v208, v208
	v_rcp_f32_e32 v209, v209
	v_lshlrev_b32_e32 v218, 16, v158
	v_and_b32_e32 v219, 0xffff0000, v158
	v_lshlrev_b32_e32 v158, 16, v159
	v_and_b32_e32 v159, 0xffff0000, v159
	v_rcp_f32_e32 v216, v216
	v_rcp_f32_e32 v217, v217
	v_mul_f32_e32 v158, v214, v158
	v_mul_f32_e32 v159, v215, v159
	v_rcp_f32_e32 v192, v192
	v_rcp_f32_e32 v193, v193
	v_mul_f32_e32 v62, v62, v158
	v_mul_f32_e32 v63, v63, v159
	v_lshlrev_b32_e32 v158, 16, v160
	v_and_b32_e32 v159, 0xffff0000, v160
	v_mul_f32_e32 v158, v208, v158
	v_mul_f32_e32 v159, v209, v159
	v_mul_f32_e32 v216, v216, v218
	v_mul_f32_e32 v217, v217, v219
	v_mul_f32_e32 v56, v56, v158
	v_mul_f32_e32 v57, v57, v159
	v_lshlrev_b32_e32 v158, 16, v161
	v_and_b32_e32 v159, 0xffff0000, v161
	v_mul_f32_e32 v158, v192, v158
	v_mul_f32_e32 v159, v193, v159
	v_mul_f32_e32 v60, v60, v216
	v_mul_f32_e32 v61, v61, v217
	v_mul_f32_e32 v58, v58, v158
	v_mul_f32_e32 v59, v59, v159
.LBB0_1557:
	v_lshlrev_b32_e32 v192, 16, v186
	v_and_b32_e32 v193, 0xffff0000, v186
	v_lshlrev_b32_e32 v186, 16, v187
	v_and_b32_e32 v187, 0xffff0000, v187
	v_lshlrev_b32_e32 v160, 16, v188
	v_and_b32_e32 v161, 0xffff0000, v188
	v_lshlrev_b32_e32 v158, 16, v189
	v_and_b32_e32 v159, 0xffff0000, v189
	s_and_b64 vcc, exec, s[40:41]
	s_mov_b64 s[16:17], -1
	s_cbranch_vccnz .LBB0_1559
	v_mul_f32_e32 v188, v28, v192
	v_mul_f32_e32 v189, v29, v193
	s_mov_b64 s[16:17], 0
	v_cvt_pk_bf16_f32 v214, v188, v189
	v_mul_f32_e32 v188, v30, v186
	v_mul_f32_e32 v189, v31, v187
	s_nop 0
	v_cvt_pk_bf16_f32 v215, v188, v189
	v_mul_f32_e32 v188, v24, v160
	v_mul_f32_e32 v189, v25, v161
	s_nop 0
	v_cvt_pk_bf16_f32 v216, v188, v189
	v_mul_f32_e32 v188, v26, v158
	v_mul_f32_e32 v189, v27, v159
	s_nop 0
	v_cvt_pk_bf16_f32 v217, v188, v189
	global_store_dwordx4 v[190:191], v[214:217], off offset:256
.LBB0_1559:
	s_andn2_b64 vcc, exec, s[16:17]
	s_cbranch_vccnz .LBB0_1561
	v_rcp_f32_e32 v186, v186
	v_rcp_f32_e32 v187, v187
	v_rcp_f32_e32 v160, v160
	v_rcp_f32_e32 v161, v161
	v_lshlrev_b32_e32 v190, 16, v154
	v_and_b32_e32 v191, 0xffff0000, v154
	v_lshlrev_b32_e32 v154, 16, v155
	v_and_b32_e32 v155, 0xffff0000, v155
	v_rcp_f32_e32 v188, v192
	v_rcp_f32_e32 v189, v193
	v_mul_f32_e32 v154, v186, v154
	v_mul_f32_e32 v155, v187, v155
	v_rcp_f32_e32 v158, v158
	v_rcp_f32_e32 v159, v159
	v_mul_f32_e32 v30, v30, v154
	v_mul_f32_e32 v31, v31, v155
	v_lshlrev_b32_e32 v154, 16, v156
	v_and_b32_e32 v155, 0xffff0000, v156
	v_mul_f32_e32 v154, v160, v154
	v_mul_f32_e32 v155, v161, v155
	v_mul_f32_e32 v188, v188, v190
	v_mul_f32_e32 v189, v189, v191
	v_mul_f32_e32 v24, v24, v154
	v_mul_f32_e32 v25, v25, v155
	v_lshlrev_b32_e32 v154, 16, v157
	v_and_b32_e32 v155, 0xffff0000, v157
	v_mul_f32_e32 v154, v158, v154
	v_mul_f32_e32 v155, v159, v155
	v_mul_f32_e32 v28, v28, v188
	v_mul_f32_e32 v29, v29, v189
	v_mul_f32_e32 v26, v26, v154
	v_mul_f32_e32 v27, v27, v155
.LBB0_1561:
	v_lshlrev_b64 v[154:155], 11, v[212:213]
	v_lshl_add_u64 v[154:155], s[74:75], 0, v[154:155]
	v_lshlrev_b32_e32 v186, 16, v182
	v_and_b32_e32 v187, 0xffff0000, v182
	v_lshlrev_b32_e32 v160, 16, v183
	v_and_b32_e32 v161, 0xffff0000, v183
	v_lshlrev_b32_e32 v158, 16, v184
	v_and_b32_e32 v159, 0xffff0000, v184
	v_lshlrev_b32_e32 v156, 16, v185
	v_and_b32_e32 v157, 0xffff0000, v185
	s_mov_b64 s[16:17], -1
	s_and_b64 vcc, exec, s[40:41]
	v_lshl_add_u64 v[154:155], v[204:205], 1, v[154:155]
	s_cbranch_vccnz .LBB0_1563
	v_mul_f32_e32 v182, v52, v186
	v_mul_f32_e32 v183, v53, v187
	v_mul_f32_e32 v184, v54, v160
	v_mul_f32_e32 v185, v55, v161
	v_cvt_pk_bf16_f32 v182, v182, v183
	v_cvt_pk_bf16_f32 v183, v184, v185
	v_mul_f32_e32 v184, v48, v158
	v_mul_f32_e32 v185, v49, v159
	v_mul_f32_e32 v188, v50, v156
	v_mul_f32_e32 v189, v51, v157
	v_cvt_pk_bf16_f32 v184, v184, v185
	v_cvt_pk_bf16_f32 v185, v188, v189
	s_mov_b64 s[16:17], 0
	global_store_dwordx4 v[154:155], v[182:185], off
.LBB0_1563:
	s_andn2_b64 vcc, exec, s[16:17]
	s_cbranch_vccnz .LBB0_1565
	v_rcp_f32_e32 v160, v160
	v_rcp_f32_e32 v161, v161
	v_rcp_f32_e32 v158, v158
	v_rcp_f32_e32 v159, v159
	v_lshlrev_b32_e32 v184, 16, v150
	v_and_b32_e32 v185, 0xffff0000, v150
	v_lshlrev_b32_e32 v150, 16, v151
	v_and_b32_e32 v151, 0xffff0000, v151
	v_rcp_f32_e32 v182, v186
	v_rcp_f32_e32 v183, v187
	v_mul_f32_e32 v150, v160, v150
	v_mul_f32_e32 v151, v161, v151
	v_rcp_f32_e32 v156, v156
	v_rcp_f32_e32 v157, v157
	v_mul_f32_e32 v54, v54, v150
	v_mul_f32_e32 v55, v55, v151
	v_lshlrev_b32_e32 v150, 16, v152
	v_and_b32_e32 v151, 0xffff0000, v152
	v_mul_f32_e32 v150, v158, v150
	v_mul_f32_e32 v151, v159, v151
	v_mul_f32_e32 v182, v182, v184
	v_mul_f32_e32 v183, v183, v185
	v_mul_f32_e32 v48, v48, v150
	v_mul_f32_e32 v49, v49, v151
	v_lshlrev_b32_e32 v150, 16, v153
	v_and_b32_e32 v151, 0xffff0000, v153
	v_mul_f32_e32 v150, v156, v150
	v_mul_f32_e32 v151, v157, v151
	v_mul_f32_e32 v52, v52, v182
	v_mul_f32_e32 v53, v53, v183
	v_mul_f32_e32 v50, v50, v150
	v_mul_f32_e32 v51, v51, v151
; DI unsigned pk2(float lo, float hi) { f32x2 v = {lo, hi}; hbf2 r = __builtin_convertvector(v, hbf2); return __builtin_bit_cast(unsigned, r); }
; DI float fast_rcp(float x) { return __builtin_amdgcn_rcpf(x); }
;     DI void operator()(f32x4 (&acc)[2][2][4][2], const Unit& u, int wr, int wc, int fr, int fq, LAS unsigned char* lds) const {
;     ...
;             for (int m = 0; m < 4; ++m) {
;                 const int row = row0 + ai * 128 + m * 16;
; #pragma unroll
;                 for (int bj = 0; bj < 2; ++bj) {
;                     const u32x4 gb = gbv[m][bj];
;                     float gbf[8];
; #pragma unroll
;                     for (int q = 0; q < 4; ++q) { gbf[2 * q] = __uint_as_float(gb[q] << 16); gbf[2 * q + 1] = __uint_as_float(gb[q] & 0xffff0000u); }
;                     if (s == 0) {
;                         const u32x4 ga = gav[m][bj];
; #pragma unroll
;                         for (int q = 0; q < 4; ++q) {
;                             const float a0 = __uint_as_float(ga[q] << 16), a1 = __uint_as_float(ga[q] & 0xffff0000u);
;                             const int n = q >> 1, j = (q & 1) * 2;
;                             acc[ai][bj][m][n][j] *= a0 * fast_rcp(gbf[2 * q]); acc[ai][bj][m][n][j + 1] *= a1 * fast_rcp(gbf[2 * q + 1]);
;                         }
;                     } else {
;                         u32x4 w;
; #pragma unroll
;                         for (int q = 0; q < 4; ++q) { const int n = q >> 1, j = (q & 1) * 2; w[q] = pk2(acc[ai][bj][m][n][j] * gbf[2 * q], acc[ai][bj][m][n][j + 1] * gbf[2 * q + 1]); }
;                         *(u32x4*)(MB + (size_t)row * DM + col0 + bj * 128) = w;
;                     }
.LBB0_1565:
	v_lshlrev_b32_e32 v158, 16, v178
	v_and_b32_e32 v159, 0xffff0000, v178
	v_lshlrev_b32_e32 v156, 16, v179
	v_and_b32_e32 v157, 0xffff0000, v179
	v_lshlrev_b32_e32 v152, 16, v180
	v_and_b32_e32 v153, 0xffff0000, v180
	v_lshlrev_b32_e32 v150, 16, v181
	v_and_b32_e32 v151, 0xffff0000, v181
	s_and_b64 vcc, exec, s[40:41]
	s_mov_b64 s[16:17], -1
	s_cbranch_vccnz .LBB0_1567
	v_mul_f32_e32 v160, v20, v158
	v_mul_f32_e32 v161, v21, v159
	s_mov_b64 s[16:17], 0
	v_cvt_pk_bf16_f32 v178, v160, v161
	v_mul_f32_e32 v160, v22, v156
	v_mul_f32_e32 v161, v23, v157
	s_nop 0
	v_cvt_pk_bf16_f32 v179, v160, v161
	v_mul_f32_e32 v160, v16, v152
	v_mul_f32_e32 v161, v17, v153
	s_nop 0
	v_cvt_pk_bf16_f32 v180, v160, v161
	v_mul_f32_e32 v160, v18, v150
	v_mul_f32_e32 v161, v19, v151
	s_nop 0
	v_cvt_pk_bf16_f32 v181, v160, v161
	global_store_dwordx4 v[154:155], v[178:181], off offset:256
.LBB0_1567:
	s_andn2_b64 vcc, exec, s[16:17]
	s_cbranch_vccnz .LBB0_1569
	v_rcp_f32_e32 v156, v156
	v_rcp_f32_e32 v157, v157
	v_rcp_f32_e32 v152, v152
	v_rcp_f32_e32 v153, v153
	v_rcp_f32_e32 v154, v158
	v_rcp_f32_e32 v155, v159
	v_lshlrev_b32_e32 v158, 16, v146
	v_and_b32_e32 v159, 0xffff0000, v146
	v_lshlrev_b32_e32 v146, 16, v147
	v_and_b32_e32 v147, 0xffff0000, v147
	v_mul_f32_e32 v146, v156, v146
	v_mul_f32_e32 v147, v157, v147
	v_rcp_f32_e32 v150, v150
	v_rcp_f32_e32 v151, v151
	v_mul_f32_e32 v22, v22, v146
	v_mul_f32_e32 v23, v23, v147
	v_lshlrev_b32_e32 v146, 16, v148
	v_and_b32_e32 v147, 0xffff0000, v148
	v_mul_f32_e32 v146, v152, v146
	v_mul_f32_e32 v147, v153, v147
	v_mul_f32_e32 v154, v154, v158
	v_mul_f32_e32 v155, v155, v159
	v_mul_f32_e32 v16, v16, v146
	v_mul_f32_e32 v17, v17, v147
	v_lshlrev_b32_e32 v146, 16, v149
	v_and_b32_e32 v147, 0xffff0000, v149
	v_mul_f32_e32 v146, v150, v146
	v_mul_f32_e32 v147, v151, v147
	v_mul_f32_e32 v20, v20, v154
	v_mul_f32_e32 v21, v21, v155
	v_mul_f32_e32 v18, v18, v146
	v_mul_f32_e32 v19, v19, v147
.LBB0_1569:
	v_lshlrev_b64 v[146:147], 11, v[210:211]
	v_lshl_add_u64 v[146:147], s[74:75], 0, v[146:147]
	v_lshlrev_b32_e32 v154, 16, v174
	v_and_b32_e32 v155, 0xffff0000, v174
	v_lshlrev_b32_e32 v152, 16, v175
	v_and_b32_e32 v153, 0xffff0000, v175
	v_lshlrev_b32_e32 v150, 16, v176
	v_and_b32_e32 v151, 0xffff0000, v176
	v_lshlrev_b32_e32 v148, 16, v177
	v_and_b32_e32 v149, 0xffff0000, v177
	s_mov_b64 s[16:17], -1
	s_and_b64 vcc, exec, s[40:41]
	v_lshl_add_u64 v[146:147], v[204:205], 1, v[146:147]
	s_cbranch_vccnz .LBB0_1571
	v_mul_f32_e32 v156, v44, v154
	v_mul_f32_e32 v157, v45, v155
	v_mul_f32_e32 v158, v46, v152
	v_mul_f32_e32 v159, v47, v153
	v_cvt_pk_bf16_f32 v156, v156, v157
	v_cvt_pk_bf16_f32 v157, v158, v159
	v_mul_f32_e32 v158, v40, v150
	v_mul_f32_e32 v159, v41, v151
	v_mul_f32_e32 v160, v42, v148
	v_mul_f32_e32 v161, v43, v149
	v_cvt_pk_bf16_f32 v158, v158, v159
	v_cvt_pk_bf16_f32 v159, v160, v161
	s_mov_b64 s[16:17], 0
	global_store_dwordx4 v[146:147], v[156:159], off
.LBB0_1571:
	s_andn2_b64 vcc, exec, s[16:17]
	s_cbranch_vccnz .LBB0_1573
	v_rcp_f32_e32 v152, v152
	v_rcp_f32_e32 v153, v153
	v_rcp_f32_e32 v150, v150
	v_rcp_f32_e32 v151, v151
	v_lshlrev_b32_e32 v156, 16, v142
	v_and_b32_e32 v157, 0xffff0000, v142
	v_lshlrev_b32_e32 v142, 16, v143
	v_and_b32_e32 v143, 0xffff0000, v143
	v_rcp_f32_e32 v154, v154
	v_rcp_f32_e32 v155, v155
	v_mul_f32_e32 v142, v152, v142
	v_mul_f32_e32 v143, v153, v143
	v_rcp_f32_e32 v148, v148
	v_rcp_f32_e32 v149, v149
	v_mul_f32_e32 v46, v46, v142
	v_mul_f32_e32 v47, v47, v143
	v_lshlrev_b32_e32 v142, 16, v144
	v_and_b32_e32 v143, 0xffff0000, v144
	v_mul_f32_e32 v142, v150, v142
	v_mul_f32_e32 v143, v151, v143
	v_mul_f32_e32 v154, v154, v156
	v_mul_f32_e32 v155, v155, v157
	v_mul_f32_e32 v40, v40, v142
	v_mul_f32_e32 v41, v41, v143
	v_lshlrev_b32_e32 v142, 16, v145
	v_and_b32_e32 v143, 0xffff0000, v145
	v_mul_f32_e32 v142, v148, v142
	v_mul_f32_e32 v143, v149, v143
	v_mul_f32_e32 v44, v44, v154
	v_mul_f32_e32 v45, v45, v155
	v_mul_f32_e32 v42, v42, v142
	v_mul_f32_e32 v43, v43, v143
; DI unsigned pk2(float lo, float hi) { f32x2 v = {lo, hi}; hbf2 r = __builtin_convertvector(v, hbf2); return __builtin_bit_cast(unsigned, r); }
; DI float fast_rcp(float x) { return __builtin_amdgcn_rcpf(x); }
;     DI void operator()(f32x4 (&acc)[2][2][4][2], const Unit& u, int wr, int wc, int fr, int fq, LAS unsigned char* lds) const {
;     ...
;             for (int m = 0; m < 4; ++m) {
;                 const int row = row0 + ai * 128 + m * 16;
; #pragma unroll
;                 for (int bj = 0; bj < 2; ++bj) {
;                     const u32x4 gb = gbv[m][bj];
;                     float gbf[8];
; #pragma unroll
;                     for (int q = 0; q < 4; ++q) { gbf[2 * q] = __uint_as_float(gb[q] << 16); gbf[2 * q + 1] = __uint_as_float(gb[q] & 0xffff0000u); }
;                     if (s == 0) {
;                         const u32x4 ga = gav[m][bj];
; #pragma unroll
;                         for (int q = 0; q < 4; ++q) {
;                             const float a0 = __uint_as_float(ga[q] << 16), a1 = __uint_as_float(ga[q] & 0xffff0000u);
;                             const int n = q >> 1, j = (q & 1) * 2;
;                             acc[ai][bj][m][n][j] *= a0 * fast_rcp(gbf[2 * q]); acc[ai][bj][m][n][j + 1] *= a1 * fast_rcp(gbf[2 * q + 1]);
;                         }
;                     } else {
;                         u32x4 w;
; #pragma unroll
;                         for (int q = 0; q < 4; ++q) { const int n = q >> 1, j = (q & 1) * 2; w[q] = pk2(acc[ai][bj][m][n][j] * gbf[2 * q], acc[ai][bj][m][n][j + 1] * gbf[2 * q + 1]); }
;                         *(u32x4*)(MB + (size_t)row * DM + col0 + bj * 128) = w;
;                     }
.LBB0_1573:
	v_lshlrev_b32_e32 v150, 16, v170
	v_and_b32_e32 v151, 0xffff0000, v170
	v_lshlrev_b32_e32 v148, 16, v171
	v_and_b32_e32 v149, 0xffff0000, v171
	v_lshlrev_b32_e32 v144, 16, v172
	v_and_b32_e32 v145, 0xffff0000, v172
	v_lshlrev_b32_e32 v142, 16, v173
	v_and_b32_e32 v143, 0xffff0000, v173
	s_and_b64 vcc, exec, s[40:41]
	s_mov_b64 s[16:17], -1
	s_cbranch_vccnz .LBB0_1575
	v_mul_f32_e32 v152, v12, v150
	v_mul_f32_e32 v153, v13, v151
	v_mul_f32_e32 v154, v14, v148
	v_mul_f32_e32 v155, v15, v149
	v_cvt_pk_bf16_f32 v152, v152, v153
	v_cvt_pk_bf16_f32 v153, v154, v155
	v_mul_f32_e32 v154, v8, v144
	v_mul_f32_e32 v155, v9, v145
	v_mul_f32_e32 v156, v10, v142
	v_mul_f32_e32 v157, v11, v143
	v_cvt_pk_bf16_f32 v154, v154, v155
	v_cvt_pk_bf16_f32 v155, v156, v157
	s_mov_b64 s[16:17], 0
	global_store_dwordx4 v[146:147], v[152:155], off offset:256
.LBB0_1575:
	s_andn2_b64 vcc, exec, s[16:17]
	s_cbranch_vccnz .LBB0_1577
	v_rcp_f32_e32 v148, v148
	v_rcp_f32_e32 v149, v149
	v_rcp_f32_e32 v144, v144
	v_rcp_f32_e32 v145, v145
	v_rcp_f32_e32 v146, v150
	v_rcp_f32_e32 v147, v151
	v_lshlrev_b32_e32 v150, 16, v138
	v_and_b32_e32 v151, 0xffff0000, v138
	v_lshlrev_b32_e32 v138, 16, v139
	v_and_b32_e32 v139, 0xffff0000, v139
	v_mul_f32_e32 v138, v148, v138
	v_mul_f32_e32 v139, v149, v139
	v_rcp_f32_e32 v142, v142
	v_rcp_f32_e32 v143, v143
	v_mul_f32_e32 v14, v14, v138
	v_mul_f32_e32 v15, v15, v139
	v_lshlrev_b32_e32 v138, 16, v140
	v_and_b32_e32 v139, 0xffff0000, v140
	v_mul_f32_e32 v138, v144, v138
	v_mul_f32_e32 v139, v145, v139
	v_mul_f32_e32 v146, v146, v150
	v_mul_f32_e32 v147, v147, v151
	v_mul_f32_e32 v8, v8, v138
	v_mul_f32_e32 v9, v9, v139
	v_lshlrev_b32_e32 v138, 16, v141
	v_and_b32_e32 v139, 0xffff0000, v141
	v_mul_f32_e32 v138, v142, v138
	v_mul_f32_e32 v139, v143, v139
	v_mul_f32_e32 v12, v12, v146
	v_mul_f32_e32 v13, v13, v147
	v_mul_f32_e32 v10, v10, v138
	v_mul_f32_e32 v11, v11, v139
.LBB0_1577:
	v_lshlrev_b64 v[138:139], 11, v[206:207]
	v_lshl_add_u64 v[138:139], s[74:75], 0, v[138:139]
	v_lshlrev_b32_e32 v146, 16, v166
	v_and_b32_e32 v147, 0xffff0000, v166
	v_lshlrev_b32_e32 v144, 16, v167
	v_and_b32_e32 v145, 0xffff0000, v167
	v_lshlrev_b32_e32 v142, 16, v168
	v_and_b32_e32 v143, 0xffff0000, v168
	v_lshlrev_b32_e32 v140, 16, v169
	v_and_b32_e32 v141, 0xffff0000, v169
	s_mov_b64 s[16:17], -1
	s_and_b64 vcc, exec, s[40:41]
	v_lshl_add_u64 v[138:139], v[204:205], 1, v[138:139]
	s_cbranch_vccnz .LBB0_1579
	v_mul_f32_e32 v148, v36, v146
	v_mul_f32_e32 v149, v37, v147
	v_mul_f32_e32 v150, v38, v144
	v_mul_f32_e32 v151, v39, v145
	v_cvt_pk_bf16_f32 v148, v148, v149
	v_cvt_pk_bf16_f32 v149, v150, v151
	v_mul_f32_e32 v150, v32, v142
	v_mul_f32_e32 v151, v33, v143
	v_mul_f32_e32 v152, v34, v140
	v_mul_f32_e32 v153, v35, v141
	v_cvt_pk_bf16_f32 v150, v150, v151
	v_cvt_pk_bf16_f32 v151, v152, v153
	s_mov_b64 s[16:17], 0
	global_store_dwordx4 v[138:139], v[148:151], off
.LBB0_1579:
	s_andn2_b64 vcc, exec, s[16:17]
	s_cbranch_vccnz .LBB0_1581
	v_rcp_f32_e32 v144, v144
	v_rcp_f32_e32 v145, v145
	v_rcp_f32_e32 v142, v142
	v_rcp_f32_e32 v143, v143
	v_lshlrev_b32_e32 v148, 16, v134
	v_and_b32_e32 v149, 0xffff0000, v134
	v_lshlrev_b32_e32 v134, 16, v135
	v_and_b32_e32 v135, 0xffff0000, v135
	v_rcp_f32_e32 v146, v146
	v_rcp_f32_e32 v147, v147
	v_mul_f32_e32 v134, v144, v134
	v_mul_f32_e32 v135, v145, v135
	v_rcp_f32_e32 v140, v140
	v_rcp_f32_e32 v141, v141
	v_mul_f32_e32 v38, v38, v134
	v_mul_f32_e32 v39, v39, v135
	v_lshlrev_b32_e32 v134, 16, v136
	v_and_b32_e32 v135, 0xffff0000, v136
	v_mul_f32_e32 v134, v142, v134
	v_mul_f32_e32 v135, v143, v135
	v_mul_f32_e32 v146, v146, v148
	v_mul_f32_e32 v147, v147, v149
	v_mul_f32_e32 v32, v32, v134
	v_mul_f32_e32 v33, v33, v135
	v_lshlrev_b32_e32 v134, 16, v137
	v_and_b32_e32 v135, 0xffff0000, v137
	v_mul_f32_e32 v134, v140, v134
	v_mul_f32_e32 v135, v141, v135
	v_mul_f32_e32 v36, v36, v146
	v_mul_f32_e32 v37, v37, v147
	v_mul_f32_e32 v34, v34, v134
	v_mul_f32_e32 v35, v35, v135
.LBB0_1581:
	v_lshlrev_b32_e32 v142, 16, v162
	v_and_b32_e32 v143, 0xffff0000, v162
	v_lshlrev_b32_e32 v140, 16, v163
	v_and_b32_e32 v141, 0xffff0000, v163
	v_lshlrev_b32_e32 v136, 16, v164
	v_and_b32_e32 v137, 0xffff0000, v164
	v_lshlrev_b32_e32 v134, 16, v165
	v_and_b32_e32 v135, 0xffff0000, v165
	s_and_b64 vcc, exec, s[40:41]
	s_mov_b64 s[16:17], -1
	s_cbranch_vccnz .LBB0_1592
	v_mul_f32_e32 v144, v4, v142
	v_mul_f32_e32 v145, v5, v143
	v_mul_f32_e32 v146, v6, v140
	v_mul_f32_e32 v147, v7, v141
	v_cvt_pk_bf16_f32 v144, v144, v145
	v_cvt_pk_bf16_f32 v145, v146, v147
	v_mul_f32_e32 v146, v0, v136
	v_mul_f32_e32 v147, v1, v137
	v_mul_f32_e32 v148, v2, v134
	v_mul_f32_e32 v149, v3, v135
	v_cvt_pk_bf16_f32 v146, v146, v147
	v_cvt_pk_bf16_f32 v147, v148, v149
	global_store_dwordx4 v[138:139], v[144:147], off offset:256
	s_cbranch_execz .LBB0_1593

; DI float fast_rcp(float x) { return __builtin_amdgcn_rcpf(x); }
;     DI void operator()(f32x4 (&acc)[2][2][4][2], const Unit& u, int wr, int wc, int fr, int fq, LAS unsigned char* lds) const {
;     ...
;                         const u32x4 ga = gav[m][bj];
; #pragma unroll
;                         for (int q = 0; q < 4; ++q) {
;                             const float a0 = __uint_as_float(ga[q] << 16), a1 = __uint_as_float(ga[q] & 0xffff0000u);
;                             const int n = q >> 1, j = (q & 1) * 2;
;                             acc[ai][bj][m][n][j] *= a0 * fast_rcp(gbf[2 * q]); acc[ai][bj][m][n][j + 1] *= a1 * fast_rcp(gbf[2 * q + 1]);
;                         }
.LBB0_1593:
	v_rcp_f32_e32 v140, v140
	v_rcp_f32_e32 v141, v141
	v_rcp_f32_e32 v136, v136
	v_rcp_f32_e32 v137, v137
	v_rcp_f32_e32 v138, v142
	v_rcp_f32_e32 v139, v143
	v_lshlrev_b32_e32 v142, 16, v130
	v_and_b32_e32 v143, 0xffff0000, v130
	v_lshlrev_b32_e32 v130, 16, v131
	v_and_b32_e32 v131, 0xffff0000, v131
	v_mul_f32_e32 v130, v140, v130
	v_mul_f32_e32 v131, v141, v131
	v_rcp_f32_e32 v134, v134
	v_rcp_f32_e32 v135, v135
	v_mul_f32_e32 v6, v6, v130
	v_mul_f32_e32 v7, v7, v131
	v_lshlrev_b32_e32 v130, 16, v132
	v_and_b32_e32 v131, 0xffff0000, v132
	v_mul_f32_e32 v130, v136, v130
	v_mul_f32_e32 v131, v137, v131
	v_mul_f32_e32 v138, v138, v142
	v_mul_f32_e32 v139, v139, v143
	v_mul_f32_e32 v0, v0, v130
	v_mul_f32_e32 v1, v1, v131
	v_lshlrev_b32_e32 v130, 16, v133
	v_and_b32_e32 v131, 0xffff0000, v133
	v_mul_f32_e32 v130, v134, v130
	v_mul_f32_e32 v131, v135, v131
	v_mul_f32_e32 v4, v4, v138
	v_mul_f32_e32 v5, v5, v139
	v_mul_f32_e32 v2, v2, v130
	v_mul_f32_e32 v3, v3, v131
	s_and_b64 vcc, exec, s[38:39]
	s_mov_b64 s[16:17], -1
	s_cbranch_vccnz .LBB0_1480

; #define PG8_STAGE(bufoff, gbase, voff) do { _Pragma("unroll") for (int _i = 0; _i < 2; ++_i) \
;         __builtin_amdgcn_global_load_lds((const unsigned*)((const char*)(gbase) + (voff)[_i]), (LAS unsigned*)(lds + (bufoff) + ldsw + _i * 8192), 16, 0, 0); } while (0)
; #define PG8_LDA(dst, b, h) do { _Pragma("unroll") for (int m = 0; m < 4; ++m) _Pragma("unroll") for (int k = 0; k < 2; ++k) dst[m][k] = *(const LAS bf16x8*)(lds + PG8_SA(b, h) + aoff + m * 2048 + k * 1024); } while (0)
; #define PG8_LDB(dst, b, h) do { _Pragma("unroll") for (int n = 0; n < 2; ++n) _Pragma("unroll") for (int k = 0; k < 2; ++k) dst[n][k] = *(const LAS bf16x8*)(lds + PG8_SB(b, h) + boff + n * 2048 + k * 1024); } while (0)
; #define PG8_MMA(ai, bj, At, Bt) do { __builtin_amdgcn_s_setprio(1); _Pragma("unroll") for (int m = 0; m < 4; ++m) _Pragma("unroll") for (int n = 0; n < 2; ++n) _Pragma("unroll") for (int k = 0; k < 2; ++k) \
;         acc[ai][bj][m][n] = __builtin_amdgcn_mfma_f32_16x16x32_bf16(Bt[n][k], At[m][k], acc[ai][bj][m][n], 0, 0, 0); __builtin_amdgcn_s_setprio(0); } while (0)
; #define PG8_WAIT_L(n) asm volatile("s_waitcnt lgkmcnt(" #n ")" ::: "memory")
; #define PG8_BAR __builtin_amdgcn_s_barrier()
; #define PG8_SCHED __builtin_amdgcn_sched_barrier(0)
; template <class Epi, class Sched>
; DI void gemm_phase(LAS unsigned char* lds, const Gemm g, const Sched& S, const Epi& E) {
;     ...
;             PG8_LDB(B0, 1, 0); PG8_SCHED; PG8_LDA(At, 1, 0); PG8_STAGE(PG8_SA(0, 1), a2 + hstep, voffA);
;             PG8_WAIT_L(8); PG8_BAR; PG8_WAIT_L(0); PG8_MMA(0, 0, At, B0); PG8_BAR; PG8_SCHED;
;             PG8_LDB(B1, 1, 1); PG8_STAGE(PG8_SB(1, 0), b3, voffB);
;             PG8_BAR; PG8_WAIT_L(0); PG8_MMA(0, 1, At, B1); PG8_BAR;
;             PG8_LDA(At, 1, 1); PG8_STAGE(PG8_SA(1, 0), a3, voffA);
;             PG8_BAR; PG8_WAIT_L(0); PG8_MMA(1, 0, At, B0); PG8_BAR; PG8_SCHED;
.Lkmid_22849:
	s_add_i32 s42, 0, 0x18000
	v_add_u32_e32 v142, s42, v198
	s_barrier
	ds_read_b128 v[130:133], v142
	ds_read_b128 v[134:137], v142 offset:1024
	ds_read_b128 v[138:141], v142 offset:2048
	ds_read_b128 v[142:145], v142 offset:3072
	s_add_u32 s0, s22, 0x40000
	s_addc_u32 s1, s23, 0
	s_mov_b32 m0, s24
	v_lshl_add_u64 v[184:185], s[0:1], 0, v[96:97]
	ds_read_b128 v[146:149], v200 offset:32768
	ds_read_b128 v[150:153], v200 offset:33792
	ds_read_b128 v[154:157], v200 offset:34816
	ds_read_b128 v[158:161], v200 offset:35840
	ds_read_b128 v[162:165], v200 offset:36864
	ds_read_b128 v[166:169], v200 offset:37888
	ds_read_b128 v[170:173], v200 offset:38912
	ds_read_b128 v[174:177], v200 offset:39936
	global_load_lds_dwordx4 v[184:185], off
	v_lshl_add_u64 v[184:185], s[0:1], 0, v[178:179]
	s_mov_b32 m0, s25
	s_nop 0
	global_load_lds_dwordx4 v[184:185], off
	s_waitcnt lgkmcnt(8)
	s_barrier
	s_waitcnt lgkmcnt(0)
	s_setprio 1
	s_waitcnt lgkmcnt(0)
	v_mfma_f32_16x16x32_bf16 v[126:129], v[130:133], v[146:149], v[126:129]
	v_mfma_f32_16x16x32_bf16 v[122:125], v[138:141], v[146:149], v[122:125]
	v_mfma_f32_16x16x32_bf16 v[110:113], v[130:133], v[154:157], v[110:113]
	v_mfma_f32_16x16x32_bf16 v[106:109], v[138:141], v[154:157], v[106:109]
	v_mfma_f32_16x16x32_bf16 v[92:95], v[130:133], v[162:165], v[92:95]
	v_mfma_f32_16x16x32_bf16 v[88:91], v[138:141], v[162:165], v[88:91]
	v_mfma_f32_16x16x32_bf16 v[76:79], v[130:133], v[170:173], v[76:79]
	v_mfma_f32_16x16x32_bf16 v[72:75], v[138:141], v[170:173], v[72:75]
	v_mfma_f32_16x16x32_bf16 v[126:129], v[134:137], v[150:153], v[126:129]
	v_mfma_f32_16x16x32_bf16 v[122:125], v[142:145], v[150:153], v[122:125]
	v_mfma_f32_16x16x32_bf16 v[110:113], v[134:137], v[158:161], v[110:113]
	v_mfma_f32_16x16x32_bf16 v[106:109], v[142:145], v[158:161], v[106:109]
	v_mfma_f32_16x16x32_bf16 v[92:95], v[134:137], v[166:169], v[92:95]
	v_mfma_f32_16x16x32_bf16 v[88:91], v[142:145], v[166:169], v[88:91]
	v_mfma_f32_16x16x32_bf16 v[76:79], v[134:137], v[174:177], v[76:79]
	v_mfma_f32_16x16x32_bf16 v[72:75], v[142:145], v[174:177], v[72:75]
	s_setprio 0
	s_barrier
	s_add_i32 s22, 0, 0x1c000
	s_add_i32 s0, s42, s5
	v_add_u32_e32 v196, s22, v198
	v_lshl_add_u64 v[206:207], v[206:207], 0, s[36:37]
	s_mov_b32 m0, s0
	ds_read_b128 v[184:187], v196
	ds_read_b128 v[188:191], v196 offset:1024
	ds_read_b128 v[192:195], v196 offset:2048
	ds_read_b128 v[202:205], v196 offset:3072
	global_load_lds_dwordx4 v[206:207], off
	v_lshl_add_u64 v[206:207], v[208:209], 0, s[36:37]
	s_add_i32 m0, s0, 0x2000
	s_nop 0
	global_load_lds_dwordx4 v[206:207], off
	s_barrier
	s_waitcnt lgkmcnt(0)
	s_setprio 1
	s_waitcnt lgkmcnt(0)
	v_mfma_f32_16x16x32_bf16 v[118:121], v[184:187], v[146:149], v[118:121]
	v_mfma_f32_16x16x32_bf16 v[114:117], v[192:195], v[146:149], v[114:117]
	v_mfma_f32_16x16x32_bf16 v[102:105], v[184:187], v[154:157], v[102:105]
	v_mfma_f32_16x16x32_bf16 v[98:101], v[192:195], v[154:157], v[98:101]
	v_mfma_f32_16x16x32_bf16 v[84:87], v[184:187], v[162:165], v[84:87]
	v_mfma_f32_16x16x32_bf16 v[80:83], v[192:195], v[162:165], v[80:83]
	v_mfma_f32_16x16x32_bf16 v[68:71], v[184:187], v[170:173], v[68:71]
	v_mfma_f32_16x16x32_bf16 v[64:67], v[192:195], v[170:173], v[64:67]
	v_mfma_f32_16x16x32_bf16 v[118:121], v[188:191], v[150:153], v[118:121]
	v_mfma_f32_16x16x32_bf16 v[114:117], v[202:205], v[150:153], v[114:117]
	v_mfma_f32_16x16x32_bf16 v[102:105], v[188:191], v[158:161], v[102:105]
	v_mfma_f32_16x16x32_bf16 v[98:101], v[202:205], v[158:161], v[98:101]
	v_mfma_f32_16x16x32_bf16 v[84:87], v[188:191], v[166:169], v[84:87]
	v_mfma_f32_16x16x32_bf16 v[80:83], v[202:205], v[166:169], v[80:83]
	v_mfma_f32_16x16x32_bf16 v[68:71], v[188:191], v[174:177], v[68:71]
	v_mfma_f32_16x16x32_bf16 v[64:67], v[202:205], v[174:177], v[64:67]
	s_setprio 0
	s_mov_b32 m0, s27
	v_lshl_add_u64 v[206:207], v[210:211], 0, s[36:37]
	s_barrier
	ds_read_b128 v[146:149], v200 offset:49152
	ds_read_b128 v[150:153], v200 offset:50176
	ds_read_b128 v[154:157], v200 offset:51200
	ds_read_b128 v[158:161], v200 offset:52224
	ds_read_b128 v[162:165], v200 offset:53248
	ds_read_b128 v[166:169], v200 offset:54272
	ds_read_b128 v[170:173], v200 offset:55296
	ds_read_b128 v[174:177], v200 offset:56320
	global_load_lds_dwordx4 v[206:207], off
	v_lshl_add_u64 v[206:207], v[212:213], 0, s[36:37]
	s_mov_b32 m0, s28
	s_nop 0
	global_load_lds_dwordx4 v[206:207], off
	s_barrier
	s_waitcnt lgkmcnt(0)
	s_setprio 1
	s_waitcnt lgkmcnt(0)
	v_mfma_f32_16x16x32_bf16 v[60:63], v[130:133], v[146:149], v[60:63]
	v_mfma_f32_16x16x32_bf16 v[56:59], v[138:141], v[146:149], v[56:59]
	v_mfma_f32_16x16x32_bf16 v[44:47], v[130:133], v[154:157], v[44:47]
	v_mfma_f32_16x16x32_bf16 v[40:43], v[138:141], v[154:157], v[40:43]
	v_mfma_f32_16x16x32_bf16 v[28:31], v[130:133], v[162:165], v[28:31]
	v_mfma_f32_16x16x32_bf16 v[24:27], v[138:141], v[162:165], v[24:27]
	v_mfma_f32_16x16x32_bf16 v[12:15], v[130:133], v[170:173], v[12:15]
	v_mfma_f32_16x16x32_bf16 v[8:11], v[138:141], v[170:173], v[8:11]
	v_mfma_f32_16x16x32_bf16 v[60:63], v[134:137], v[150:153], v[60:63]
	v_mfma_f32_16x16x32_bf16 v[56:59], v[142:145], v[150:153], v[56:59]
	v_mfma_f32_16x16x32_bf16 v[44:47], v[134:137], v[158:161], v[44:47]
	v_mfma_f32_16x16x32_bf16 v[40:43], v[142:145], v[158:161], v[40:43]
	v_mfma_f32_16x16x32_bf16 v[28:31], v[134:137], v[166:169], v[28:31]
	v_mfma_f32_16x16x32_bf16 v[24:27], v[142:145], v[166:169], v[24:27]
	v_mfma_f32_16x16x32_bf16 v[12:15], v[134:137], v[174:177], v[12:15]
	v_mfma_f32_16x16x32_bf16 v[8:11], v[142:145], v[174:177], v[8:11]
	s_setprio 0
	s_barrier
; #define LAS __attribute__((address_space(3)))
; #define PG8_STAGE(bufoff, gbase, voff) do { _Pragma("unroll") for (int _i = 0; _i < 2; ++_i) \
;         __builtin_amdgcn_global_load_lds((const unsigned*)((const char*)(gbase) + (voff)[_i]), (LAS unsigned*)(lds + (bufoff) + ldsw + _i * 8192), 16, 0, 0); } while (0)
; #define PG8_MMA(ai, bj, At, Bt) do { __builtin_amdgcn_s_setprio(1); _Pragma("unroll") for (int m = 0; m < 4; ++m) _Pragma("unroll") for (int n = 0; n < 2; ++n) _Pragma("unroll") for (int k = 0; k < 2; ++k) \
;         acc[ai][bj][m][n] = __builtin_amdgcn_mfma_f32_16x16x32_bf16(Bt[n][k], At[m][k], acc[ai][bj][m][n], 0, 0, 0); __builtin_amdgcn_s_setprio(0); } while (0)
; #define PG8_WAIT_V(n) asm volatile("s_waitcnt vmcnt(" #n ")" ::: "memory")
; #define PG8_BAR __builtin_amdgcn_s_barrier()
; template <class Epi, class Sched>
; DI void gemm_phase(LAS unsigned char* lds, const Gemm g, const Sched& S, const Epi& E) {
;     ...
;             PG8_STAGE(PG8_SB(1, 1), b3 + hstep, voffB);
;             PG8_WAIT_V(6); PG8_BAR; PG8_MMA(1, 1, At, B1); PG8_BAR;
;     DI void operator()(f32x4 (&acc)[2][2][4][2], const Unit& u, int wr, int wc, int fr, int fq, LAS unsigned char* lds) const {
;         const int row0 = u.pm * 256 + wr * 64 + fr, col0 = u.pn * 256 + wc * 32 + 4 * fq;
; #pragma unroll
;         for (int ai = 0; ai < 2; ++ai) {
;             f32x4 xv[4][2][2];
; #pragma unroll
;             for (int m = 0; m < 4; ++m) {
;                 const int row = row0 + ai * 128 + m * 16;
;                 const float* xi = (row < TP ? xin_p + (size_t)row * DM : xin_s + (size_t)(row - TP) * DM) + col0;
; #pragma unroll
;                 for (int bj = 0; bj < 2; ++bj)
; #pragma unroll
;                     for (int n = 0; n < 2; ++n) xv[m][bj][n] = *(const f32x4*)(xi + bj * 128 + n * 16);
;             }
	s_add_u32 s0, s20, 0x40080
	s_addc_u32 s1, s21, 0
	s_add_i32 s20, s22, s5
	v_lshl_add_u64 v[130:131], s[0:1], 0, v[96:97]
	s_mov_b32 m0, s20
	s_nop 0
	global_load_lds_dwordx4 v[130:131], off
	v_lshl_add_u64 v[130:131], s[0:1], 0, v[178:179]
	s_add_i32 m0, s20, 0x2000
	s_nop 0
	global_load_lds_dwordx4 v[130:131], off
	s_waitcnt vmcnt(6)
	s_barrier
	s_setprio 1
	v_mfma_f32_16x16x32_bf16 v[52:55], v[184:187], v[146:149], v[52:55]
	v_mfma_f32_16x16x32_bf16 v[48:51], v[192:195], v[146:149], v[48:51]
	v_mfma_f32_16x16x32_bf16 v[36:39], v[184:187], v[154:157], v[36:39]
	v_mfma_f32_16x16x32_bf16 v[32:35], v[192:195], v[154:157], v[32:35]
	v_mfma_f32_16x16x32_bf16 v[20:23], v[184:187], v[162:165], v[20:23]
	v_mfma_f32_16x16x32_bf16 v[16:19], v[192:195], v[162:165], v[16:19]
	v_mfma_f32_16x16x32_bf16 v[4:7], v[184:187], v[170:173], v[4:7]
	v_mfma_f32_16x16x32_bf16 v[0:3], v[192:195], v[170:173], v[0:3]
	v_mfma_f32_16x16x32_bf16 v[52:55], v[188:191], v[150:153], v[52:55]
	v_mfma_f32_16x16x32_bf16 v[48:51], v[202:205], v[150:153], v[48:51]
	v_mfma_f32_16x16x32_bf16 v[36:39], v[188:191], v[158:161], v[36:39]
	v_mfma_f32_16x16x32_bf16 v[32:35], v[202:205], v[158:161], v[32:35]
	v_mfma_f32_16x16x32_bf16 v[20:23], v[188:191], v[166:169], v[20:23]
	v_mfma_f32_16x16x32_bf16 v[16:19], v[202:205], v[166:169], v[16:19]
	v_mfma_f32_16x16x32_bf16 v[4:7], v[188:191], v[174:177], v[4:7]
	v_mfma_f32_16x16x32_bf16 v[0:3], v[202:205], v[174:177], v[0:3]
	s_setprio 0
	s_add_i32 s41, s41, 2
	s_add_u32 s18, s18, 0x100
	s_addc_u32 s19, s19, 0
	s_add_u32 s34, s34, 0x100
	s_addc_u32 s40, s40, 0
	s_cmp_lt_u32 s41, 14
	s_barrier
	s_cbranch_scc1 .LBB0_1684
	v_lshl_add_u32 v186, s2, 8, v197
	v_add_u32_e32 v130, 0xffff8000, v186
	v_ashrrev_i32_e32 v187, 31, v186
	v_cmp_gt_i32_e32 vcc, s86, v186
	v_lshl_or_b32 v184, s30, 8, v199
	v_mov_b32_e32 v134, s63
	v_cndmask_b32_e32 v131, 0, v187, vcc
	v_cndmask_b32_e32 v130, v130, v186, vcc
	v_mov_b32_e32 v135, s91
	v_mov_b32_e32 v136, s62
	v_mov_b32_e32 v137, s90
	v_ashrrev_i32_e32 v185, 31, v184
	v_cndmask_b32_e32 v133, v134, v135, vcc
	v_cndmask_b32_e32 v132, v136, v137, vcc
	v_lshlrev_b64 v[130:131], 12, v[130:131]
	v_lshl_add_u64 v[130:131], v[132:133], 0, v[130:131]
	v_lshlrev_b64 v[188:189], 2, v[184:185]
	v_lshl_add_u64 v[130:131], v[130:131], 0, v[188:189]
	global_load_dwordx4 v[204:207], v[130:131], off
	global_load_dwordx4 v[208:211], v[130:131], off offset:64
	global_load_dwordx4 v[212:215], v[130:131], off offset:512
	global_load_dwordx4 v[216:219], v[130:131], off offset:576
	v_or_b32_e32 v194, 16, v186
	v_ashrrev_i32_e32 v195, 31, v194
	v_add_u32_e32 v130, 0xffff8010, v186
	v_cmp_gt_i32_e32 vcc, s86, v194
	v_or_b32_e32 v192, 32, v186
	v_ashrrev_i32_e32 v193, 31, v192
	v_cndmask_b32_e32 v131, 0, v195, vcc
	v_cndmask_b32_e32 v130, v130, v194, vcc
	v_cndmask_b32_e32 v133, v134, v135, vcc
	v_cndmask_b32_e32 v132, v136, v137, vcc
	v_lshlrev_b64 v[130:131], 12, v[130:131]
	v_lshl_add_u64 v[130:131], v[132:133], 0, v[130:131]
	v_lshl_add_u64 v[130:131], v[130:131], 0, v[188:189]
	global_load_dwordx4 v[174:177], v[130:131], off
	global_load_dwordx4 v[170:173], v[130:131], off offset:64
	global_load_dwordx4 v[166:169], v[130:131], off offset:512
	global_load_dwordx4 v[162:165], v[130:131], off offset:576
	v_add_u32_e32 v130, 0xffff8020, v186
	v_cmp_gt_i32_e32 vcc, s86, v192
	v_or_b32_e32 v190, 48, v186
	v_ashrrev_i32_e32 v191, 31, v190
	v_cndmask_b32_e32 v131, 0, v193, vcc
	v_cndmask_b32_e32 v130, v130, v192, vcc
	v_cndmask_b32_e32 v133, v134, v135, vcc
	v_cndmask_b32_e32 v132, v136, v137, vcc
	v_lshlrev_b64 v[130:131], 12, v[130:131]
	v_lshl_add_u64 v[130:131], v[132:133], 0, v[130:131]
	v_lshl_add_u64 v[130:131], v[130:131], 0, v[188:189]
	global_load_dwordx4 v[158:161], v[130:131], off
	global_load_dwordx4 v[154:157], v[130:131], off offset:64
	global_load_dwordx4 v[150:153], v[130:131], off offset:512
	global_load_dwordx4 v[146:149], v[130:131], off offset:576
	v_add_u32_e32 v130, 0xffff8030, v186
	v_cmp_gt_i32_e32 vcc, s86, v190
	v_lshlrev_b64 v[220:221], 12, v[186:187]
	v_lshl_add_u64 v[220:221], s[90:91], 0, v[220:221]
	v_cndmask_b32_e32 v131, 0, v191, vcc
	v_cndmask_b32_e32 v130, v130, v190, vcc
	v_cndmask_b32_e32 v133, v134, v135, vcc
	v_cndmask_b32_e32 v132, v136, v137, vcc
	v_lshlrev_b64 v[130:131], 12, v[130:131]
	v_lshl_add_u64 v[130:131], v[132:133], 0, v[130:131]
	v_lshl_add_u64 v[130:131], v[130:131], 0, v[188:189]
	global_load_dwordx4 v[142:145], v[130:131], off
	global_load_dwordx4 v[138:141], v[130:131], off offset:64
	global_load_dwordx4 v[134:137], v[130:131], off offset:512
	s_nop 0
	global_load_dwordx4 v[130:133], v[130:131], off offset:576
	v_lshl_add_u64 v[220:221], v[220:221], 0, v[188:189]
	v_lshlrev_b64 v[222:223], 11, v[186:187]
	v_lshl_add_u64 v[222:223], s[72:73], 0, v[222:223]
	v_lshl_add_u64 v[222:223], v[184:185], 1, v[222:223]
	v_and_b32_e32 v201, 64, v229
	v_xor_b32_e32 v196, 16, v229
	v_add_u32_e32 v201, 64, v201
	v_cmp_lt_i32_e32 vcc, v196, v201
	v_xor_b32_e32 v202, 32, v229
	s_waitcnt vmcnt(0)
; DI unsigned pk2(float lo, float hi) { f32x2 v = {lo, hi}; hbf2 r = __builtin_convertvector(v, hbf2); return __builtin_bit_cast(unsigned, r); }
;     DI void operator()(f32x4 (&acc)[2][2][4][2], const Unit& u, int wr, int wc, int fr, int fq, LAS unsigned char* lds) const {
;     ...
; #pragma unroll
;             for (int m = 0; m < 4; ++m) {
;                 const int row = row0 + ai * 128 + m * 16;
;                 float* xo = X + (size_t)row * DM + col0; bf16_t* xb = XB + (size_t)row * DM + col0;
;                 float ssq = 0.f;
; #pragma unroll
;                 for (int bj = 0; bj < 2; ++bj)
; #pragma unroll
;                     for (int n = 0; n < 2; ++n) {
;                         const int c = bj * 128 + n * 16;
;                         const f32x4 o = xv[m][bj][n] + acc[ai][bj][m][n] * scale;
;                         *(f32x4*)(xo + c) = o;
;                         if (wxb) { u32x2 w; w.x = pk2(o[0], o[1]); w.y = pk2(o[2], o[3]); *(u32x2*)(xb + c) = w; }
;                         ssq += (o[0] * o[0] + o[1] * o[1]) + (o[2] * o[2] + o[3] * o[3]);
;                     }
;                 ssq += __shfl_xor(ssq, 16); ssq += __shfl_xor(ssq, 32);
;                 if (fq == 0) SS[(size_t)row * 16 + u.pn * 4 + wc] = ssq;
;             }
	v_add_f32_e32 v128, v128, v206
	v_add_f32_e32 v129, v129, v207
	v_add_f32_e32 v126, v126, v204
	v_add_f32_e32 v127, v127, v205
	global_store_dwordx4 v[220:221], v[126:129], off
	v_cvt_pk_bf16_f32 v204, v126, v127
	v_cvt_pk_bf16_f32 v205, v128, v129
	v_mul_f32_e32 v127, v127, v127
	v_fmac_f32_e32 v127, v126, v126
	v_mul_f32_e32 v126, v129, v129
	v_fmac_f32_e32 v126, v128, v128
	v_add_f32_e32 v124, v124, v210
	v_add_f32_e32 v125, v125, v211
	v_add_f32_e32 v122, v122, v208
	v_add_f32_e32 v123, v123, v209
	global_store_dwordx2 v[222:223], v[204:205], off
	v_add_f32_e32 v128, v127, v126
	global_store_dwordx4 v[220:221], v[122:125], off offset:64
	v_cvt_pk_bf16_f32 v126, v122, v123
	v_add_f32_e32 v120, v120, v214
	v_add_f32_e32 v121, v121, v215
	v_mul_f32_e32 v123, v123, v123
	v_fmac_f32_e32 v123, v122, v122
	v_mul_f32_e32 v122, v125, v125
	v_fmac_f32_e32 v122, v124, v124
	v_add_f32_e32 v118, v118, v212
	v_add_f32_e32 v119, v119, v213
	v_cvt_pk_bf16_f32 v127, v124, v125
	v_add_f32_e32 v122, v123, v122
	v_mul_f32_e32 v123, v119, v119
	v_mul_f32_e32 v124, v121, v121
	v_fmac_f32_e32 v123, v118, v118
	v_fmac_f32_e32 v124, v120, v120
	v_add_f32_e32 v122, v128, v122
	v_add_f32_e32 v123, v123, v124
	global_store_dwordx2 v[222:223], v[126:127], off offset:32
	v_add_f32_e32 v126, v122, v123
	v_add_f32_e32 v124, v116, v218
	v_add_f32_e32 v125, v117, v219
	v_add_f32_e32 v122, v114, v216
	v_add_f32_e32 v123, v115, v217
	v_mul_f32_e32 v115, v125, v125
	v_mul_f32_e32 v114, v123, v123
	v_fmac_f32_e32 v114, v122, v122
	v_fmac_f32_e32 v115, v124, v124
	v_cndmask_b32_e32 v196, v229, v196, vcc
	v_add_f32_e32 v114, v114, v115
	v_lshlrev_b32_e32 v196, 2, v196
	v_add_f32_e32 v116, v126, v114
	ds_bpermute_b32 v117, v196, v116
	v_cmp_lt_i32_e32 vcc, v202, v201
	v_cvt_pk_bf16_f32 v114, v118, v119
	v_cvt_pk_bf16_f32 v115, v120, v121
	v_cndmask_b32_e32 v202, v229, v202, vcc
	v_lshlrev_b32_e32 v202, 2, v202
	global_store_dwordx4 v[220:221], v[118:121], off offset:512
	global_store_dwordx2 v[222:223], v[114:115], off offset:256
	s_waitcnt lgkmcnt(0)
	v_add_f32_e32 v114, v116, v117
	ds_bpermute_b32 v115, v202, v114
	v_cvt_pk_bf16_f32 v116, v122, v123
	v_cvt_pk_bf16_f32 v117, v124, v125
	global_store_dwordx4 v[220:221], v[122:125], off offset:576
	global_store_dwordx2 v[222:223], v[116:117], off offset:288
	s_and_saveexec_b64 s[18:19], s[38:39]
	s_cbranch_execz .LBB0_1687
	s_waitcnt lgkmcnt(0)
	v_add_f32_e32 v116, v114, v115
	s_lshl_b32 s0, s30, 2
	v_lshlrev_b64 v[114:115], 6, v[186:187]
	s_ashr_i32 s1, s0, 31
	v_lshl_add_u64 v[114:115], s[70:71], 0, v[114:115]
	v_lshl_add_u64 v[114:115], s[0:1], 2, v[114:115]
	s_lshl_b32 s68, s26, 2
	v_lshl_add_u64 v[114:115], v[114:115], 0, s[68:69]
	global_store_dword v[114:115], v116, off
.LBB0_1687:
	s_or_b64 exec, exec, s[18:19]
	s_waitcnt lgkmcnt(0)
	v_lshlrev_b64 v[114:115], 12, v[194:195]
	v_lshl_add_u64 v[114:115], s[90:91], 0, v[114:115]
	v_lshl_add_u64 v[114:115], v[184:185], 2, v[114:115]
	v_add_f32_e32 v112, v112, v176
	v_add_f32_e32 v113, v113, v177
	v_add_f32_e32 v110, v110, v174
	v_add_f32_e32 v111, v111, v175
	v_lshlrev_b64 v[116:117], 11, v[194:195]
	global_store_dwordx4 v[114:115], v[110:113], off
	v_cvt_pk_bf16_f32 v118, v110, v111
	v_lshl_add_u64 v[116:117], s[72:73], 0, v[116:117]
	v_mul_f32_e32 v111, v111, v111
	v_fmac_f32_e32 v111, v110, v110
	v_mul_f32_e32 v110, v113, v113
	v_lshl_add_u64 v[116:117], v[184:185], 1, v[116:117]
	v_cvt_pk_bf16_f32 v119, v112, v113
	v_fmac_f32_e32 v110, v112, v112
	v_add_f32_e32 v108, v108, v172
	v_add_f32_e32 v109, v109, v173
	v_add_f32_e32 v106, v106, v170
	v_add_f32_e32 v107, v107, v171
	global_store_dwordx2 v[116:117], v[118:119], off
	v_add_f32_e32 v112, v111, v110
	global_store_dwordx4 v[114:115], v[106:109], off offset:64
	v_cvt_pk_bf16_f32 v110, v106, v107
	v_add_f32_e32 v104, v104, v168
	v_add_f32_e32 v105, v105, v169
	v_mul_f32_e32 v107, v107, v107
	v_fmac_f32_e32 v107, v106, v106
	v_mul_f32_e32 v106, v109, v109
	v_fmac_f32_e32 v106, v108, v108
	v_add_f32_e32 v102, v102, v166
	v_add_f32_e32 v103, v103, v167
	v_cvt_pk_bf16_f32 v111, v108, v109
	v_add_f32_e32 v106, v107, v106
	v_mul_f32_e32 v107, v103, v103
	v_mul_f32_e32 v108, v105, v105
	v_fmac_f32_e32 v107, v102, v102
	v_fmac_f32_e32 v108, v104, v104
	v_add_f32_e32 v106, v112, v106
	v_add_f32_e32 v107, v107, v108
	global_store_dwordx2 v[116:117], v[110:111], off offset:32
	v_add_f32_e32 v110, v106, v107
	v_add_f32_e32 v108, v100, v164
	v_add_f32_e32 v109, v101, v165
	v_add_f32_e32 v106, v98, v162
	v_add_f32_e32 v107, v99, v163
	v_mul_f32_e32 v99, v109, v109
	v_mul_f32_e32 v98, v107, v107
	v_fmac_f32_e32 v98, v106, v106
	v_fmac_f32_e32 v99, v108, v108
	v_add_f32_e32 v98, v98, v99
	v_add_f32_e32 v100, v110, v98
	ds_bpermute_b32 v101, v196, v100
	v_cvt_pk_bf16_f32 v98, v102, v103
	v_cvt_pk_bf16_f32 v99, v104, v105
	global_store_dwordx4 v[114:115], v[102:105], off offset:512
	global_store_dwordx2 v[116:117], v[98:99], off offset:256
	s_waitcnt lgkmcnt(0)
	v_add_f32_e32 v98, v100, v101
	ds_bpermute_b32 v99, v202, v98
	v_cvt_pk_bf16_f32 v100, v106, v107
	v_cvt_pk_bf16_f32 v101, v108, v109
	global_store_dwordx4 v[114:115], v[106:109], off offset:576
	global_store_dwordx2 v[116:117], v[100:101], off offset:288
	s_and_saveexec_b64 s[18:19], s[38:39]
	s_mov_b32 s34, s57
	s_cbranch_execz .LBB0_1689
	s_waitcnt lgkmcnt(0)
	v_add_f32_e32 v100, v98, v99
	s_lshl_b32 s0, s30, 2
	v_lshlrev_b64 v[98:99], 6, v[194:195]
	s_ashr_i32 s1, s0, 31
	v_lshl_add_u64 v[98:99], s[70:71], 0, v[98:99]
	v_lshl_add_u64 v[98:99], s[0:1], 2, v[98:99]
	s_lshl_b32 s68, s26, 2
	v_lshl_add_u64 v[98:99], v[98:99], 0, s[68:69]
	global_store_dword v[98:99], v100, off
; DI unsigned pk2(float lo, float hi) { f32x2 v = {lo, hi}; hbf2 r = __builtin_convertvector(v, hbf2); return __builtin_bit_cast(unsigned, r); }
;     DI void operator()(f32x4 (&acc)[2][2][4][2], const Unit& u, int wr, int wc, int fr, int fq, LAS unsigned char* lds) const {
;     ...
; #pragma unroll
;             for (int m = 0; m < 4; ++m) {
;                 const int row = row0 + ai * 128 + m * 16;
;                 float* xo = X + (size_t)row * DM + col0; bf16_t* xb = XB + (size_t)row * DM + col0;
;                 float ssq = 0.f;
; #pragma unroll
;                 for (int bj = 0; bj < 2; ++bj)
; #pragma unroll
;                     for (int n = 0; n < 2; ++n) {
;                         const int c = bj * 128 + n * 16;
;                         const f32x4 o = xv[m][bj][n] + acc[ai][bj][m][n] * scale;
;                         *(f32x4*)(xo + c) = o;
;                         if (wxb) { u32x2 w; w.x = pk2(o[0], o[1]); w.y = pk2(o[2], o[3]); *(u32x2*)(xb + c) = w; }
;                         ssq += (o[0] * o[0] + o[1] * o[1]) + (o[2] * o[2] + o[3] * o[3]);
;                     }
;                 ssq += __shfl_xor(ssq, 16); ssq += __shfl_xor(ssq, 32);
;                 if (fq == 0) SS[(size_t)row * 16 + u.pn * 4 + wc] = ssq;
;             }
.LBB0_1689:
	s_or_b64 exec, exec, s[18:19]
	s_waitcnt lgkmcnt(0)
	v_lshlrev_b64 v[98:99], 12, v[192:193]
	v_lshl_add_u64 v[98:99], s[90:91], 0, v[98:99]
	v_lshl_add_u64 v[98:99], v[184:185], 2, v[98:99]
	v_add_f32_e32 v94, v94, v160
	v_add_f32_e32 v95, v95, v161
	v_add_f32_e32 v92, v92, v158
	v_add_f32_e32 v93, v93, v159
	v_lshlrev_b64 v[100:101], 11, v[192:193]
	global_store_dwordx4 v[98:99], v[92:95], off
	v_cvt_pk_bf16_f32 v102, v92, v93
	v_lshl_add_u64 v[100:101], s[72:73], 0, v[100:101]
	v_mul_f32_e32 v93, v93, v93
	v_fmac_f32_e32 v93, v92, v92
	v_mul_f32_e32 v92, v95, v95
	v_lshl_add_u64 v[100:101], v[184:185], 1, v[100:101]
	v_cvt_pk_bf16_f32 v103, v94, v95
	v_fmac_f32_e32 v92, v94, v94
	v_add_f32_e32 v90, v90, v156
	v_add_f32_e32 v91, v91, v157
	v_add_f32_e32 v88, v88, v154
	v_add_f32_e32 v89, v89, v155
	global_store_dwordx2 v[100:101], v[102:103], off
	v_add_f32_e32 v94, v93, v92
	global_store_dwordx4 v[98:99], v[88:91], off offset:64
	v_cvt_pk_bf16_f32 v92, v88, v89
	v_add_f32_e32 v86, v86, v152
	v_add_f32_e32 v87, v87, v153
	v_mul_f32_e32 v89, v89, v89
	v_fmac_f32_e32 v89, v88, v88
	v_mul_f32_e32 v88, v91, v91
	v_fmac_f32_e32 v88, v90, v90
	v_add_f32_e32 v84, v84, v150
	v_add_f32_e32 v85, v85, v151
	v_cvt_pk_bf16_f32 v93, v90, v91
	v_add_f32_e32 v88, v89, v88
	v_mul_f32_e32 v89, v85, v85
	v_mul_f32_e32 v90, v87, v87
	v_fmac_f32_e32 v89, v84, v84
	v_fmac_f32_e32 v90, v86, v86
	v_add_f32_e32 v88, v94, v88
	v_add_f32_e32 v89, v89, v90
	global_store_dwordx2 v[100:101], v[92:93], off offset:32
	v_add_f32_e32 v92, v88, v89
	v_add_f32_e32 v90, v82, v148
	v_add_f32_e32 v91, v83, v149
	v_add_f32_e32 v88, v80, v146
	v_add_f32_e32 v89, v81, v147
	v_mul_f32_e32 v81, v91, v91
	v_mul_f32_e32 v80, v89, v89
	v_fmac_f32_e32 v80, v88, v88
	v_fmac_f32_e32 v81, v90, v90
	v_add_f32_e32 v80, v80, v81
	v_add_f32_e32 v82, v92, v80
	ds_bpermute_b32 v83, v196, v82
	v_cvt_pk_bf16_f32 v80, v84, v85
	v_cvt_pk_bf16_f32 v81, v86, v87
	global_store_dwordx4 v[98:99], v[84:87], off offset:512
	global_store_dwordx2 v[100:101], v[80:81], off offset:256
	s_waitcnt lgkmcnt(0)
	v_add_f32_e32 v80, v82, v83
	ds_bpermute_b32 v81, v202, v80
	v_cvt_pk_bf16_f32 v82, v88, v89
	v_cvt_pk_bf16_f32 v83, v90, v91
	global_store_dwordx4 v[98:99], v[88:91], off offset:576
	global_store_dwordx2 v[100:101], v[82:83], off offset:288
	s_and_saveexec_b64 s[18:19], s[38:39]
	s_cbranch_execz .LBB0_1691
	s_waitcnt lgkmcnt(0)
	v_add_f32_e32 v82, v80, v81
	s_lshl_b32 s0, s30, 2
	v_lshlrev_b64 v[80:81], 6, v[192:193]
	s_ashr_i32 s1, s0, 31
	v_lshl_add_u64 v[80:81], s[70:71], 0, v[80:81]
	v_lshl_add_u64 v[80:81], s[0:1], 2, v[80:81]
	s_lshl_b32 s68, s26, 2
	v_lshl_add_u64 v[80:81], v[80:81], 0, s[68:69]
	global_store_dword v[80:81], v82, off
.LBB0_1691:
	s_or_b64 exec, exec, s[18:19]
	s_waitcnt lgkmcnt(0)
	v_lshlrev_b64 v[80:81], 12, v[190:191]
	v_lshl_add_u64 v[80:81], s[90:91], 0, v[80:81]
	v_lshl_add_u64 v[80:81], v[184:185], 2, v[80:81]
	v_add_f32_e32 v78, v78, v144
	v_add_f32_e32 v79, v79, v145
	v_add_f32_e32 v76, v76, v142
	v_add_f32_e32 v77, v77, v143
	v_lshlrev_b64 v[82:83], 11, v[190:191]
	global_store_dwordx4 v[80:81], v[76:79], off
	v_cvt_pk_bf16_f32 v84, v76, v77
	v_lshl_add_u64 v[82:83], s[72:73], 0, v[82:83]
	v_mul_f32_e32 v77, v77, v77
	v_fmac_f32_e32 v77, v76, v76
	v_mul_f32_e32 v76, v79, v79
	v_lshl_add_u64 v[82:83], v[184:185], 1, v[82:83]
	v_cvt_pk_bf16_f32 v85, v78, v79
	v_fmac_f32_e32 v76, v78, v78
	v_add_f32_e32 v74, v74, v140
	v_add_f32_e32 v75, v75, v141
	v_add_f32_e32 v72, v72, v138
	v_add_f32_e32 v73, v73, v139
	global_store_dwordx2 v[82:83], v[84:85], off
	v_add_f32_e32 v78, v77, v76
	global_store_dwordx4 v[80:81], v[72:75], off offset:64
	v_cvt_pk_bf16_f32 v76, v72, v73
	v_add_f32_e32 v70, v70, v136
	v_add_f32_e32 v71, v71, v137
	v_mul_f32_e32 v73, v73, v73
	v_fmac_f32_e32 v73, v72, v72
	v_mul_f32_e32 v72, v75, v75
	v_fmac_f32_e32 v72, v74, v74
	v_add_f32_e32 v68, v68, v134
	v_add_f32_e32 v69, v69, v135
	v_cvt_pk_bf16_f32 v77, v74, v75
	v_add_f32_e32 v72, v73, v72
	v_mul_f32_e32 v73, v69, v69
	v_mul_f32_e32 v74, v71, v71
	v_fmac_f32_e32 v73, v68, v68
	v_fmac_f32_e32 v74, v70, v70
	v_add_f32_e32 v72, v78, v72
	v_add_f32_e32 v73, v73, v74
	global_store_dwordx2 v[82:83], v[76:77], off offset:32
	v_add_f32_e32 v76, v72, v73
	v_add_f32_e32 v74, v66, v132
	v_add_f32_e32 v75, v67, v133
	v_add_f32_e32 v72, v64, v130
	v_add_f32_e32 v73, v65, v131
	v_mul_f32_e32 v65, v75, v75
	v_mul_f32_e32 v64, v73, v73
	v_fmac_f32_e32 v64, v72, v72
	v_fmac_f32_e32 v65, v74, v74
	v_add_f32_e32 v64, v64, v65
	v_add_f32_e32 v66, v76, v64
	ds_bpermute_b32 v67, v196, v66
	v_cvt_pk_bf16_f32 v64, v68, v69
	v_cvt_pk_bf16_f32 v65, v70, v71
	global_store_dwordx4 v[80:81], v[68:71], off offset:512
	global_store_dwordx2 v[82:83], v[64:65], off offset:256
	s_waitcnt lgkmcnt(0)
	v_add_f32_e32 v64, v66, v67
	ds_bpermute_b32 v65, v202, v64
	v_cvt_pk_bf16_f32 v66, v72, v73
	v_cvt_pk_bf16_f32 v67, v74, v75
	global_store_dwordx4 v[80:81], v[72:75], off offset:576
	global_store_dwordx2 v[82:83], v[66:67], off offset:288
	s_and_saveexec_b64 s[18:19], s[38:39]
	s_cbranch_execz .LBB0_1693
	s_waitcnt lgkmcnt(0)
	v_add_f32_e32 v66, v64, v65
	s_lshl_b32 s0, s30, 2
	v_lshlrev_b64 v[64:65], 6, v[190:191]
	s_ashr_i32 s1, s0, 31
	v_lshl_add_u64 v[64:65], s[70:71], 0, v[64:65]
	v_lshl_add_u64 v[64:65], s[0:1], 2, v[64:65]
	s_lshl_b32 s68, s26, 2
	v_lshl_add_u64 v[64:65], v[64:65], 0, s[68:69]
	global_store_dword v[64:65], v66, off
; DI unsigned pk2(float lo, float hi) { f32x2 v = {lo, hi}; hbf2 r = __builtin_convertvector(v, hbf2); return __builtin_bit_cast(unsigned, r); }
;     DI void operator()(f32x4 (&acc)[2][2][4][2], const Unit& u, int wr, int wc, int fr, int fq, LAS unsigned char* lds) const {
;     ...
;             for (int m = 0; m < 4; ++m) {
;                 const int row = row0 + ai * 128 + m * 16;
;                 const float* xi = (row < TP ? xin_p + (size_t)row * DM : xin_s + (size_t)(row - TP) * DM) + col0;
; #pragma unroll
;                 for (int bj = 0; bj < 2; ++bj)
; #pragma unroll
;                     for (int n = 0; n < 2; ++n) xv[m][bj][n] = *(const f32x4*)(xi + bj * 128 + n * 16);
;             }
; #pragma unroll
;             for (int m = 0; m < 4; ++m) {
;                 const int row = row0 + ai * 128 + m * 16;
;                 float* xo = X + (size_t)row * DM + col0; bf16_t* xb = XB + (size_t)row * DM + col0;
;                 float ssq = 0.f;
; #pragma unroll
;                 for (int bj = 0; bj < 2; ++bj)
; #pragma unroll
;                     for (int n = 0; n < 2; ++n) {
;                         const int c = bj * 128 + n * 16;
;                         const f32x4 o = xv[m][bj][n] + acc[ai][bj][m][n] * scale;
;                         *(f32x4*)(xo + c) = o;
;                         if (wxb) { u32x2 w; w.x = pk2(o[0], o[1]); w.y = pk2(o[2], o[3]); *(u32x2*)(xb + c) = w; }
;                         ssq += (o[0] * o[0] + o[1] * o[1]) + (o[2] * o[2] + o[3] * o[3]);
;                     }
;                 ssq += __shfl_xor(ssq, 16); ssq += __shfl_xor(ssq, 32);
;                 if (fq == 0) SS[(size_t)row * 16 + u.pn * 4 + wc] = ssq;
;             }
.LBB0_1693:
	s_or_b64 exec, exec, s[18:19]
	v_add_u32_e32 v128, 0x80, v186
	s_movk_i32 s0, 0x7f80
	v_cmp_gt_i32_e32 vcc, s0, v186
	v_ashrrev_i32_e32 v129, 31, v128
	v_add_u32_e32 v64, 0xffff8080, v186
	s_waitcnt lgkmcnt(0)
	v_cndmask_b32_e32 v65, 0, v129, vcc
	v_cndmask_b32_e32 v64, v64, v128, vcc
	v_mov_b32_e32 v68, s63
	v_mov_b32_e32 v69, s91
	v_mov_b32_e32 v70, s62
	v_mov_b32_e32 v71, s90
	v_cndmask_b32_e32 v67, v68, v69, vcc
	v_cndmask_b32_e32 v66, v70, v71, vcc
	v_lshlrev_b64 v[64:65], 12, v[64:65]
	v_lshl_add_u64 v[64:65], v[66:67], 0, v[64:65]
	v_lshl_add_u64 v[64:65], v[64:65], 0, v[188:189]
	global_load_dwordx4 v[130:133], v[64:65], off
	global_load_dwordx4 v[134:137], v[64:65], off offset:64
	global_load_dwordx4 v[118:121], v[64:65], off offset:512
	global_load_dwordx4 v[114:117], v[64:65], off offset:576
	v_add_u32_e32 v126, 0x90, v186
	s_movk_i32 s0, 0x7f70
	v_cmp_gt_i32_e32 vcc, s0, v186
	v_ashrrev_i32_e32 v127, 31, v126
	v_add_u32_e32 v64, 0xffff8090, v186
	v_cndmask_b32_e32 v65, 0, v127, vcc
	v_cndmask_b32_e32 v64, v64, v126, vcc
	v_cndmask_b32_e32 v67, v68, v69, vcc
	v_cndmask_b32_e32 v66, v70, v71, vcc
	v_lshlrev_b64 v[64:65], 12, v[64:65]
	v_lshl_add_u64 v[64:65], v[66:67], 0, v[64:65]
	v_lshl_add_u64 v[64:65], v[64:65], 0, v[188:189]
	v_add_u32_e32 v124, 0xa0, v186
	s_movk_i32 s0, 0x7f60
	global_load_dwordx4 v[110:113], v[64:65], off
	global_load_dwordx4 v[106:109], v[64:65], off offset:64
	global_load_dwordx4 v[102:105], v[64:65], off offset:512
	global_load_dwordx4 v[98:101], v[64:65], off offset:576
	v_cmp_gt_i32_e32 vcc, s0, v186
	v_ashrrev_i32_e32 v125, 31, v124
	v_add_u32_e32 v64, 0xffff80a0, v186
	v_cndmask_b32_e32 v65, 0, v125, vcc
	v_cndmask_b32_e32 v64, v64, v124, vcc
	v_cndmask_b32_e32 v67, v68, v69, vcc
	v_cndmask_b32_e32 v66, v70, v71, vcc
	v_lshlrev_b64 v[64:65], 12, v[64:65]
	v_lshl_add_u64 v[64:65], v[66:67], 0, v[64:65]
	v_lshl_add_u64 v[64:65], v[64:65], 0, v[188:189]
	v_add_u32_e32 v122, 0xb0, v186
	s_movk_i32 s0, 0x7f50
	global_load_dwordx4 v[92:95], v[64:65], off
	global_load_dwordx4 v[88:91], v[64:65], off offset:64
	global_load_dwordx4 v[84:87], v[64:65], off offset:512
	global_load_dwordx4 v[80:83], v[64:65], off offset:576
	v_cmp_gt_i32_e32 vcc, s0, v186
	v_ashrrev_i32_e32 v123, 31, v122
	v_add_u32_e32 v64, 0xffff80b0, v186
	v_cndmask_b32_e32 v65, 0, v123, vcc
	v_cndmask_b32_e32 v64, v64, v122, vcc
	v_cndmask_b32_e32 v67, v68, v69, vcc
	v_cndmask_b32_e32 v66, v70, v71, vcc
	v_lshlrev_b64 v[64:65], 12, v[64:65]
	v_lshl_add_u64 v[64:65], v[66:67], 0, v[64:65]
	v_lshl_add_u64 v[64:65], v[64:65], 0, v[188:189]
	global_load_dwordx4 v[76:79], v[64:65], off
	global_load_dwordx4 v[72:75], v[64:65], off offset:64
	global_load_dwordx4 v[68:71], v[64:65], off offset:512
	s_nop 0
	global_load_dwordx4 v[64:67], v[64:65], off offset:576
	v_lshlrev_b64 v[138:139], 12, v[128:129]
	v_lshl_add_u64 v[138:139], s[90:91], 0, v[138:139]
	v_lshl_add_u64 v[138:139], v[138:139], 0, v[188:189]
	v_lshlrev_b64 v[140:141], 11, v[128:129]
	v_lshl_add_u64 v[140:141], s[72:73], 0, v[140:141]
	v_lshl_add_u64 v[140:141], v[184:185], 1, v[140:141]
	s_waitcnt vmcnt(15)
	v_add_f32_e32 v62, v62, v132
	v_add_f32_e32 v63, v63, v133
	v_add_f32_e32 v60, v60, v130
	v_add_f32_e32 v61, v61, v131
	global_store_dwordx4 v[138:139], v[60:63], off
	v_cvt_pk_bf16_f32 v130, v60, v61
	v_cvt_pk_bf16_f32 v131, v62, v63
	v_mul_f32_e32 v61, v61, v61
	v_fmac_f32_e32 v61, v60, v60
	v_mul_f32_e32 v60, v63, v63
	v_fmac_f32_e32 v60, v62, v62
	s_waitcnt vmcnt(15)
	v_add_f32_e32 v58, v58, v136
	v_add_f32_e32 v59, v59, v137
	v_add_f32_e32 v56, v56, v134
	v_add_f32_e32 v57, v57, v135
	global_store_dwordx2 v[140:141], v[130:131], off
	v_add_f32_e32 v62, v61, v60
	global_store_dwordx4 v[138:139], v[56:59], off offset:64
	v_cvt_pk_bf16_f32 v60, v56, v57
	v_cvt_pk_bf16_f32 v61, v58, v59
	v_mul_f32_e32 v57, v57, v57
	v_fmac_f32_e32 v57, v56, v56
	v_mul_f32_e32 v56, v59, v59
	v_fmac_f32_e32 v56, v58, v58
	v_add_f32_e32 v56, v57, v56
	s_waitcnt vmcnt(16)
	v_add_f32_e32 v54, v54, v120
	v_add_f32_e32 v55, v55, v121
	v_add_f32_e32 v52, v52, v118
	v_add_f32_e32 v53, v53, v119
	global_store_dwordx2 v[140:141], v[60:61], off offset:32
	v_add_f32_e32 v58, v62, v56
	global_store_dwordx4 v[138:139], v[52:55], off offset:512
	v_cvt_pk_bf16_f32 v56, v52, v53
	v_cvt_pk_bf16_f32 v57, v54, v55
	v_mul_f32_e32 v53, v53, v53
	v_fmac_f32_e32 v53, v52, v52
	v_mul_f32_e32 v52, v55, v55
	v_fmac_f32_e32 v52, v54, v54
	v_add_f32_e32 v52, v53, v52
	s_waitcnt vmcnt(17)
	v_add_f32_e32 v50, v50, v116
	v_add_f32_e32 v51, v51, v117
	v_add_f32_e32 v48, v48, v114
	v_add_f32_e32 v49, v49, v115
	global_store_dwordx2 v[140:141], v[56:57], off offset:256
	v_add_f32_e32 v54, v58, v52
	global_store_dwordx4 v[138:139], v[48:51], off offset:576
	v_cvt_pk_bf16_f32 v52, v48, v49
	v_cvt_pk_bf16_f32 v53, v50, v51
	v_mul_f32_e32 v49, v49, v49
	v_fmac_f32_e32 v49, v48, v48
	v_mul_f32_e32 v48, v51, v51
	v_fmac_f32_e32 v48, v50, v50
	v_add_f32_e32 v48, v49, v48
	v_add_f32_e32 v48, v54, v48
	ds_bpermute_b32 v49, v196, v48
	global_store_dwordx2 v[140:141], v[52:53], off offset:288
	s_waitcnt lgkmcnt(0)
	v_add_f32_e32 v48, v48, v49
	ds_bpermute_b32 v49, v202, v48
	s_and_saveexec_b64 s[18:19], s[38:39]
	s_cbranch_execz .LBB0_1695
	s_waitcnt lgkmcnt(0)
	v_add_f32_e32 v50, v48, v49
	s_lshl_b32 s0, s30, 2
	v_lshlrev_b64 v[48:49], 6, v[128:129]
	s_ashr_i32 s1, s0, 31
	v_lshl_add_u64 v[48:49], s[70:71], 0, v[48:49]
	v_lshl_add_u64 v[48:49], s[0:1], 2, v[48:49]
	s_lshl_b32 s68, s26, 2
	v_lshl_add_u64 v[48:49], v[48:49], 0, s[68:69]
	global_store_dword v[48:49], v50, off
; DI unsigned pk2(float lo, float hi) { f32x2 v = {lo, hi}; hbf2 r = __builtin_convertvector(v, hbf2); return __builtin_bit_cast(unsigned, r); }
;     DI void operator()(f32x4 (&acc)[2][2][4][2], const Unit& u, int wr, int wc, int fr, int fq, LAS unsigned char* lds) const {
;     ...
; #pragma unroll
;             for (int m = 0; m < 4; ++m) {
;                 const int row = row0 + ai * 128 + m * 16;
;                 float* xo = X + (size_t)row * DM + col0; bf16_t* xb = XB + (size_t)row * DM + col0;
;                 float ssq = 0.f;
; #pragma unroll
;                 for (int bj = 0; bj < 2; ++bj)
; #pragma unroll
;                     for (int n = 0; n < 2; ++n) {
;                         const int c = bj * 128 + n * 16;
;                         const f32x4 o = xv[m][bj][n] + acc[ai][bj][m][n] * scale;
;                         *(f32x4*)(xo + c) = o;
;                         if (wxb) { u32x2 w; w.x = pk2(o[0], o[1]); w.y = pk2(o[2], o[3]); *(u32x2*)(xb + c) = w; }
;                         ssq += (o[0] * o[0] + o[1] * o[1]) + (o[2] * o[2] + o[3] * o[3]);
;                     }
;                 ssq += __shfl_xor(ssq, 16); ssq += __shfl_xor(ssq, 32);
;                 if (fq == 0) SS[(size_t)row * 16 + u.pn * 4 + wc] = ssq;
;             }
.LBB0_1695:
	s_or_b64 exec, exec, s[18:19]
	s_waitcnt lgkmcnt(0)
	v_lshlrev_b64 v[48:49], 12, v[126:127]
	v_lshl_add_u64 v[48:49], s[90:91], 0, v[48:49]
	v_lshl_add_u64 v[48:49], v[184:185], 2, v[48:49]
	s_waitcnt vmcnt(19)
	v_add_f32_e32 v46, v46, v112
	v_add_f32_e32 v47, v47, v113
	v_add_f32_e32 v44, v44, v110
	v_add_f32_e32 v45, v45, v111
	v_lshlrev_b64 v[50:51], 11, v[126:127]
	global_store_dwordx4 v[48:49], v[44:47], off
	v_cvt_pk_bf16_f32 v52, v44, v45
	v_lshl_add_u64 v[50:51], s[72:73], 0, v[50:51]
	v_mul_f32_e32 v45, v45, v45
	v_fmac_f32_e32 v45, v44, v44
	v_mul_f32_e32 v44, v47, v47
	v_lshl_add_u64 v[50:51], v[184:185], 1, v[50:51]
	v_cvt_pk_bf16_f32 v53, v46, v47
	v_fmac_f32_e32 v44, v46, v46
	s_waitcnt vmcnt(19)
	v_add_f32_e32 v42, v42, v108
	v_add_f32_e32 v43, v43, v109
	v_add_f32_e32 v40, v40, v106
	v_add_f32_e32 v41, v41, v107
	global_store_dwordx2 v[50:51], v[52:53], off
	v_add_f32_e32 v46, v45, v44
	global_store_dwordx4 v[48:49], v[40:43], off offset:64
	v_cvt_pk_bf16_f32 v44, v40, v41
	s_waitcnt vmcnt(20)
	v_add_f32_e32 v38, v38, v104
	v_add_f32_e32 v39, v39, v105
	v_mul_f32_e32 v41, v41, v41
	v_fmac_f32_e32 v41, v40, v40
	v_mul_f32_e32 v40, v43, v43
	v_fmac_f32_e32 v40, v42, v42
	v_add_f32_e32 v36, v36, v102
	v_add_f32_e32 v37, v37, v103
	v_cvt_pk_bf16_f32 v45, v42, v43
	v_add_f32_e32 v40, v41, v40
	v_mul_f32_e32 v41, v37, v37
	v_mul_f32_e32 v42, v39, v39
	v_fmac_f32_e32 v41, v36, v36
	v_fmac_f32_e32 v42, v38, v38
	v_add_f32_e32 v40, v46, v40
	v_add_f32_e32 v41, v41, v42
	global_store_dwordx2 v[50:51], v[44:45], off offset:32
	v_add_f32_e32 v44, v40, v41
	s_waitcnt vmcnt(20)
	v_add_f32_e32 v42, v34, v100
	v_add_f32_e32 v43, v35, v101
	v_add_f32_e32 v40, v32, v98
	v_add_f32_e32 v41, v33, v99
	v_mul_f32_e32 v33, v43, v43
	v_mul_f32_e32 v32, v41, v41
	v_fmac_f32_e32 v32, v40, v40
	v_fmac_f32_e32 v33, v42, v42
	v_add_f32_e32 v32, v32, v33
	v_add_f32_e32 v34, v44, v32
	ds_bpermute_b32 v35, v196, v34
	v_cvt_pk_bf16_f32 v32, v36, v37
	v_cvt_pk_bf16_f32 v33, v38, v39
	global_store_dwordx4 v[48:49], v[36:39], off offset:512
	global_store_dwordx2 v[50:51], v[32:33], off offset:256
	s_waitcnt lgkmcnt(0)
	v_add_f32_e32 v32, v34, v35
	ds_bpermute_b32 v33, v202, v32
	v_cvt_pk_bf16_f32 v34, v40, v41
	v_cvt_pk_bf16_f32 v35, v42, v43
	global_store_dwordx4 v[48:49], v[40:43], off offset:576
	global_store_dwordx2 v[50:51], v[34:35], off offset:288
	s_and_saveexec_b64 s[18:19], s[38:39]
	s_cbranch_execz .LBB0_1697
	s_waitcnt lgkmcnt(0)
	v_add_f32_e32 v34, v32, v33
	s_lshl_b32 s0, s30, 2
	v_lshlrev_b64 v[32:33], 6, v[126:127]
	s_ashr_i32 s1, s0, 31
	v_lshl_add_u64 v[32:33], s[70:71], 0, v[32:33]
	v_lshl_add_u64 v[32:33], s[0:1], 2, v[32:33]
	s_lshl_b32 s68, s26, 2
	v_lshl_add_u64 v[32:33], v[32:33], 0, s[68:69]
	global_store_dword v[32:33], v34, off
; DI unsigned pk2(float lo, float hi) { f32x2 v = {lo, hi}; hbf2 r = __builtin_convertvector(v, hbf2); return __builtin_bit_cast(unsigned, r); }
;     DI void operator()(f32x4 (&acc)[2][2][4][2], const Unit& u, int wr, int wc, int fr, int fq, LAS unsigned char* lds) const {
;     ...
; #pragma unroll
;             for (int m = 0; m < 4; ++m) {
;                 const int row = row0 + ai * 128 + m * 16;
;                 float* xo = X + (size_t)row * DM + col0; bf16_t* xb = XB + (size_t)row * DM + col0;
;                 float ssq = 0.f;
; #pragma unroll
;                 for (int bj = 0; bj < 2; ++bj)
; #pragma unroll
;                     for (int n = 0; n < 2; ++n) {
;                         const int c = bj * 128 + n * 16;
;                         const f32x4 o = xv[m][bj][n] + acc[ai][bj][m][n] * scale;
;                         *(f32x4*)(xo + c) = o;
;                         if (wxb) { u32x2 w; w.x = pk2(o[0], o[1]); w.y = pk2(o[2], o[3]); *(u32x2*)(xb + c) = w; }
;                         ssq += (o[0] * o[0] + o[1] * o[1]) + (o[2] * o[2] + o[3] * o[3]);
;                     }
;                 ssq += __shfl_xor(ssq, 16); ssq += __shfl_xor(ssq, 32);
;                 if (fq == 0) SS[(size_t)row * 16 + u.pn * 4 + wc] = ssq;
;             }
.LBB0_1697:
	s_or_b64 exec, exec, s[18:19]
	s_waitcnt lgkmcnt(0)
	v_lshlrev_b64 v[32:33], 12, v[124:125]
	v_lshl_add_u64 v[32:33], s[90:91], 0, v[32:33]
	v_lshl_add_u64 v[32:33], v[184:185], 2, v[32:33]
	s_waitcnt vmcnt(23)
	v_add_f32_e32 v30, v30, v94
	v_add_f32_e32 v31, v31, v95
	v_add_f32_e32 v28, v28, v92
	v_add_f32_e32 v29, v29, v93
	v_lshlrev_b64 v[34:35], 11, v[124:125]
	global_store_dwordx4 v[32:33], v[28:31], off
	v_cvt_pk_bf16_f32 v36, v28, v29
	v_lshl_add_u64 v[34:35], s[72:73], 0, v[34:35]
	v_mul_f32_e32 v29, v29, v29
	v_fmac_f32_e32 v29, v28, v28
	v_mul_f32_e32 v28, v31, v31
	v_lshl_add_u64 v[34:35], v[184:185], 1, v[34:35]
	v_cvt_pk_bf16_f32 v37, v30, v31
	v_fmac_f32_e32 v28, v30, v30
	s_waitcnt vmcnt(23)
	v_add_f32_e32 v26, v26, v90
	v_add_f32_e32 v27, v27, v91
	v_add_f32_e32 v24, v24, v88
	v_add_f32_e32 v25, v25, v89
	global_store_dwordx2 v[34:35], v[36:37], off
	v_add_f32_e32 v30, v29, v28
	global_store_dwordx4 v[32:33], v[24:27], off offset:64
	v_cvt_pk_bf16_f32 v28, v24, v25
	s_waitcnt vmcnt(24)
	v_add_f32_e32 v22, v22, v86
	v_add_f32_e32 v23, v23, v87
	v_mul_f32_e32 v25, v25, v25
	v_fmac_f32_e32 v25, v24, v24
	v_mul_f32_e32 v24, v27, v27
	v_fmac_f32_e32 v24, v26, v26
	v_add_f32_e32 v20, v20, v84
	v_add_f32_e32 v21, v21, v85
	v_cvt_pk_bf16_f32 v29, v26, v27
	v_add_f32_e32 v24, v25, v24
	v_mul_f32_e32 v25, v21, v21
	v_mul_f32_e32 v26, v23, v23
	v_fmac_f32_e32 v25, v20, v20
	v_fmac_f32_e32 v26, v22, v22
	v_add_f32_e32 v24, v30, v24
	v_add_f32_e32 v25, v25, v26
	global_store_dwordx2 v[34:35], v[28:29], off offset:32
	v_add_f32_e32 v28, v24, v25
	s_waitcnt vmcnt(24)
	v_add_f32_e32 v26, v18, v82
	v_add_f32_e32 v27, v19, v83
	v_add_f32_e32 v24, v16, v80
	v_add_f32_e32 v25, v17, v81
	v_mul_f32_e32 v17, v27, v27
	v_mul_f32_e32 v16, v25, v25
	v_fmac_f32_e32 v16, v24, v24
	v_fmac_f32_e32 v17, v26, v26
	v_add_f32_e32 v16, v16, v17
	v_add_f32_e32 v18, v28, v16
	ds_bpermute_b32 v19, v196, v18
	v_cvt_pk_bf16_f32 v16, v20, v21
	v_cvt_pk_bf16_f32 v17, v22, v23
	global_store_dwordx4 v[32:33], v[20:23], off offset:512
	global_store_dwordx2 v[34:35], v[16:17], off offset:256
	s_waitcnt lgkmcnt(0)
	v_add_f32_e32 v16, v18, v19
	ds_bpermute_b32 v17, v202, v16
	v_cvt_pk_bf16_f32 v18, v24, v25
	v_cvt_pk_bf16_f32 v19, v26, v27
	global_store_dwordx4 v[32:33], v[24:27], off offset:576
	global_store_dwordx2 v[34:35], v[18:19], off offset:288
	s_and_saveexec_b64 s[18:19], s[38:39]
	s_cbranch_execz .LBB0_1699
	s_waitcnt lgkmcnt(0)
	v_add_f32_e32 v18, v16, v17
	s_lshl_b32 s0, s30, 2
	v_lshlrev_b64 v[16:17], 6, v[124:125]
	s_ashr_i32 s1, s0, 31
	v_lshl_add_u64 v[16:17], s[70:71], 0, v[16:17]
	v_lshl_add_u64 v[16:17], s[0:1], 2, v[16:17]
	s_lshl_b32 s68, s26, 2
	v_lshl_add_u64 v[16:17], v[16:17], 0, s[68:69]
	global_store_dword v[16:17], v18, off
.LBB0_1699:
	s_or_b64 exec, exec, s[18:19]
	s_waitcnt lgkmcnt(0)
	v_lshlrev_b64 v[16:17], 12, v[122:123]
	v_lshl_add_u64 v[16:17], s[90:91], 0, v[16:17]
	v_lshl_add_u64 v[16:17], v[184:185], 2, v[16:17]
	s_waitcnt vmcnt(27)
	v_add_f32_e32 v14, v14, v78
	v_add_f32_e32 v15, v15, v79
	v_add_f32_e32 v12, v12, v76
	v_add_f32_e32 v13, v13, v77
	v_lshlrev_b64 v[18:19], 11, v[122:123]
	global_store_dwordx4 v[16:17], v[12:15], off
	v_cvt_pk_bf16_f32 v20, v12, v13
	v_lshl_add_u64 v[18:19], s[72:73], 0, v[18:19]
	v_mul_f32_e32 v13, v13, v13
	v_fmac_f32_e32 v13, v12, v12
	v_mul_f32_e32 v12, v15, v15
	v_lshl_add_u64 v[18:19], v[184:185], 1, v[18:19]
	v_cvt_pk_bf16_f32 v21, v14, v15
	v_fmac_f32_e32 v12, v14, v14
	s_waitcnt vmcnt(27)
	v_add_f32_e32 v10, v10, v74
	v_add_f32_e32 v11, v11, v75
	v_add_f32_e32 v8, v8, v72
	v_add_f32_e32 v9, v9, v73
	global_store_dwordx2 v[18:19], v[20:21], off
	v_add_f32_e32 v14, v13, v12
	global_store_dwordx4 v[16:17], v[8:11], off offset:64
	v_cvt_pk_bf16_f32 v12, v8, v9
	s_waitcnt vmcnt(28)
	v_add_f32_e32 v6, v6, v70
	v_add_f32_e32 v7, v7, v71
	v_mul_f32_e32 v9, v9, v9
	v_fmac_f32_e32 v9, v8, v8
	v_mul_f32_e32 v8, v11, v11
	v_fmac_f32_e32 v8, v10, v10
	v_add_f32_e32 v4, v4, v68
	v_add_f32_e32 v5, v5, v69
	v_cvt_pk_bf16_f32 v13, v10, v11
	v_add_f32_e32 v8, v9, v8
	v_mul_f32_e32 v9, v5, v5
	v_mul_f32_e32 v10, v7, v7
	v_fmac_f32_e32 v9, v4, v4
	v_fmac_f32_e32 v10, v6, v6
	v_add_f32_e32 v8, v14, v8
	v_add_f32_e32 v9, v9, v10
	global_store_dwordx2 v[18:19], v[12:13], off offset:32
	v_add_f32_e32 v12, v8, v9
	s_waitcnt vmcnt(28)
	v_add_f32_e32 v10, v2, v66
	v_add_f32_e32 v11, v3, v67
	v_add_f32_e32 v8, v0, v64
	v_add_f32_e32 v9, v1, v65
	v_mul_f32_e32 v1, v11, v11
	v_mul_f32_e32 v0, v9, v9
	v_fmac_f32_e32 v0, v8, v8
	v_fmac_f32_e32 v1, v10, v10
	v_add_f32_e32 v0, v0, v1
	v_add_f32_e32 v2, v12, v0
	ds_bpermute_b32 v3, v196, v2
	v_cvt_pk_bf16_f32 v0, v4, v5
	v_cvt_pk_bf16_f32 v1, v6, v7
	global_store_dwordx4 v[16:17], v[4:7], off offset:512
	global_store_dwordx2 v[18:19], v[0:1], off offset:256
	s_waitcnt lgkmcnt(0)
	v_add_f32_e32 v0, v2, v3
	ds_bpermute_b32 v1, v202, v0
	v_cvt_pk_bf16_f32 v2, v8, v9
	v_cvt_pk_bf16_f32 v3, v10, v11
	global_store_dwordx4 v[16:17], v[8:11], off offset:576
	global_store_dwordx2 v[18:19], v[2:3], off offset:288
	s_and_saveexec_b64 s[18:19], s[38:39]
	s_cbranch_execz .LBB0_1678
	s_waitcnt lgkmcnt(0)
	v_add_f32_e32 v2, v0, v1
	s_lshl_b32 s0, s30, 2
	v_lshlrev_b64 v[0:1], 6, v[122:123]
	s_ashr_i32 s1, s0, 31
	v_lshl_add_u64 v[0:1], s[70:71], 0, v[0:1]
	v_lshl_add_u64 v[0:1], s[0:1], 2, v[0:1]
	s_lshl_b32 s68, s26, 2
	v_lshl_add_u64 v[0:1], v[0:1], 0, s[68:69]
	global_store_dword v[0:1], v2, off
	s_branch .LBB0_1678
